# v89: conversion staggered per XCD pair over 4 slots (phase start, two unit boundaries, phase end), one shared conversion chunk, + xloc + 2 items in flight
# speedup vs baseline: 1.0015x; 1.0015x over previous
; #define REP(b) for (int rep_ = 0; rep_ < (((DUPMASK >> (b)) & 1) ? 2 : 1); ++rep_)
; __global__ void __launch_bounds__(NWAVES * 64, 2) fwd(Args args_unused) {
;     ...
;         if (IN(pb)) {
;             REP(2) { ENV(); pg8::Gemm g{(const bf16*)(ws + WS_HN), (const bf16*)(ws + WS_W + (size_t)l * W_LAYER + W_IN), M, NIN, DM, LDH, 0}; pg8::StaticOrder S; S.init(M, NIN, G, bx);
;               pg8::EpiProj E{(bf16*)(ws + WS_PROJ), (const float*)(ws + WS_COSA), (const float*)(ws + WS_SINA), (const float*)(ws + WS_COSB), (const float*)(ws + WS_SINB), (const pg8::ss_t*)(ws + WS_SS) + l * M};
;               pg8::gemm_phase<pg8::EpiProj, pg8::StaticOrder, true>(ldsp + RING_OFF, g, S, E); }
.LBB0_272:
	s_andn2_b64 vcc, exec, s[4:5]
	s_cbranch_vccnz .LBB0_354
	s_cmp_lg_u32 s71, 0
	s_cbranch_scc1 .Ldefer_skipA
	s_mov_b32 s100, 0x20180
	v_mov_b32_e32 v2, s100
	ds_read_b32 v3, v2 offset:4
	ds_read_b32 v4, v2
	ds_read_b32 v2, v2 offset:8
	s_load_dword s101, s[90:91], 0x0
	s_waitcnt lgkmcnt(0)
	v_readfirstlane_b32 s100, v2
	v_readfirstlane_b32 s98, v3
	v_readfirstlane_b32 s99, v4
	s_lshl_b32 s98, s98, 3
	s_add_i32 s98, s98, s99
	s_cmp_lg_u32 s100, 0
	s_cselect_b32 s100, s98, s77
	s_bfe_u32 s100, s100, 0x20001
	s_add_i32 s98, s100, 1
	s_cmp_eq_u32 s100, 0
	s_cselect_b32 s98, 0, s98
	s_cmp_eq_u32 s100, 3
	s_cselect_b32 s100, 5, s98
	s_cmpk_eq_i32 s101, 0x100
	s_cselect_b32 s100, s100, 0
	s_cmp_lg_u32 s100, 0
	s_cbranch_scc1 .Ldefer_skipA
	v_writelane_b32 v252, s0, 0
	v_writelane_b32 v252, s1, 1
	v_writelane_b32 v252, s2, 2
	v_writelane_b32 v252, s3, 3
	v_writelane_b32 v252, s4, 4
	v_writelane_b32 v252, s5, 5
	v_writelane_b32 v252, s6, 6
	v_writelane_b32 v252, s7, 7
	v_writelane_b32 v252, s8, 8
	v_writelane_b32 v252, s9, 9
	v_writelane_b32 v252, s10, 10
	v_writelane_b32 v252, s11, 11
	v_writelane_b32 v252, s12, 12
	v_writelane_b32 v252, s13, 13
	v_writelane_b32 v252, s14, 14
	v_writelane_b32 v252, s15, 15
	v_writelane_b32 v252, s16, 16
	v_writelane_b32 v252, s17, 17
	v_writelane_b32 v252, s18, 18
	v_writelane_b32 v252, s19, 19
	v_writelane_b32 v252, s20, 20
	v_writelane_b32 v252, s21, 21
	v_writelane_b32 v252, s22, 22
	v_writelane_b32 v252, s23, 23
	v_writelane_b32 v252, s24, 24
	v_writelane_b32 v252, s25, 25
	v_writelane_b32 v252, s26, 26
	v_writelane_b32 v252, s27, 27
	v_writelane_b32 v252, s28, 28
	v_writelane_b32 v252, s29, 29
	v_writelane_b32 v252, s30, 30
	v_writelane_b32 v252, s31, 31
	v_writelane_b32 v252, s32, 32
	v_writelane_b32 v252, s33, 33
	v_writelane_b32 v252, s34, 34
	v_writelane_b32 v252, s35, 35
	v_writelane_b32 v252, s36, 36
	v_writelane_b32 v252, s37, 37
	v_writelane_b32 v252, s38, 38
	v_writelane_b32 v252, s39, 39
	v_writelane_b32 v252, s40, 40
	v_writelane_b32 v252, s41, 41
	v_writelane_b32 v252, s42, 42
	v_writelane_b32 v252, s43, 43
	v_writelane_b32 v252, s44, 44
	v_writelane_b32 v252, s45, 45
	v_writelane_b32 v252, s46, 46
	v_writelane_b32 v252, s47, 47
	v_writelane_b32 v252, s48, 48
	v_writelane_b32 v252, s49, 49
	v_writelane_b32 v252, s50, 50
	v_writelane_b32 v252, s51, 51
	v_writelane_b32 v252, s52, 52
	v_writelane_b32 v252, s53, 53
	v_writelane_b32 v252, s54, 54
	v_writelane_b32 v252, s55, 55
	v_writelane_b32 v252, s56, 56
	v_writelane_b32 v252, s57, 57
	v_writelane_b32 v252, s58, 58
	v_writelane_b32 v252, s59, 59
	v_writelane_b32 v252, s60, 60
	v_writelane_b32 v252, s61, 61
	v_writelane_b32 v252, s62, 62
	v_writelane_b32 v252, s63, 63
	v_writelane_b32 v253, s64, 0
	v_writelane_b32 v253, s65, 1
	v_writelane_b32 v253, s66, 2
	v_writelane_b32 v253, s67, 3
	v_writelane_b32 v253, s68, 4
	v_writelane_b32 v253, s69, 5
	v_writelane_b32 v253, s70, 6
	v_writelane_b32 v253, s71, 7
	v_writelane_b32 v253, s72, 8
	v_writelane_b32 v253, s73, 9
	s_mov_b32 s101, 0
	s_branch .Lconv_shared
.Lret_A:
	s_waitcnt lgkmcnt(0)
	s_barrier
	v_readlane_b32 s0, v252, 0
	v_readlane_b32 s1, v252, 1
	v_readlane_b32 s2, v252, 2
	v_readlane_b32 s3, v252, 3
	v_readlane_b32 s4, v252, 4
	v_readlane_b32 s5, v252, 5
	v_readlane_b32 s6, v252, 6
	v_readlane_b32 s7, v252, 7
	v_readlane_b32 s8, v252, 8
	v_readlane_b32 s9, v252, 9
	v_readlane_b32 s10, v252, 10
	v_readlane_b32 s11, v252, 11
	v_readlane_b32 s12, v252, 12
	v_readlane_b32 s13, v252, 13
	v_readlane_b32 s14, v252, 14
	v_readlane_b32 s15, v252, 15
	v_readlane_b32 s16, v252, 16
	v_readlane_b32 s17, v252, 17
	v_readlane_b32 s18, v252, 18
	v_readlane_b32 s19, v252, 19
	v_readlane_b32 s20, v252, 20
	v_readlane_b32 s21, v252, 21
	v_readlane_b32 s22, v252, 22
	v_readlane_b32 s23, v252, 23
	v_readlane_b32 s24, v252, 24
	v_readlane_b32 s25, v252, 25
	v_readlane_b32 s26, v252, 26
	v_readlane_b32 s27, v252, 27
	v_readlane_b32 s28, v252, 28
	v_readlane_b32 s29, v252, 29
	v_readlane_b32 s30, v252, 30
	v_readlane_b32 s31, v252, 31
	v_readlane_b32 s32, v252, 32
	v_readlane_b32 s33, v252, 33
	v_readlane_b32 s34, v252, 34
	v_readlane_b32 s35, v252, 35
	v_readlane_b32 s36, v252, 36
	v_readlane_b32 s37, v252, 37
	v_readlane_b32 s38, v252, 38
	v_readlane_b32 s39, v252, 39
	v_readlane_b32 s40, v252, 40
	v_readlane_b32 s41, v252, 41
	v_readlane_b32 s42, v252, 42
	v_readlane_b32 s43, v252, 43
	v_readlane_b32 s44, v252, 44
	v_readlane_b32 s45, v252, 45
	v_readlane_b32 s46, v252, 46
	v_readlane_b32 s47, v252, 47
	v_readlane_b32 s48, v252, 48
	v_readlane_b32 s49, v252, 49
	v_readlane_b32 s50, v252, 50
	v_readlane_b32 s51, v252, 51
	v_readlane_b32 s52, v252, 52
	v_readlane_b32 s53, v252, 53
	v_readlane_b32 s54, v252, 54
	v_readlane_b32 s55, v252, 55
	v_readlane_b32 s56, v252, 56
	v_readlane_b32 s57, v252, 57
	v_readlane_b32 s58, v252, 58
	v_readlane_b32 s59, v252, 59
	v_readlane_b32 s60, v252, 60
	v_readlane_b32 s61, v252, 61
	v_readlane_b32 s62, v252, 62
	v_readlane_b32 s63, v252, 63
	v_readlane_b32 s64, v253, 0
	v_readlane_b32 s65, v253, 1
	v_readlane_b32 s66, v253, 2
	v_readlane_b32 s67, v253, 3
	v_readlane_b32 s68, v253, 4
	v_readlane_b32 s69, v253, 5
	v_readlane_b32 s70, v253, 6
	v_readlane_b32 s71, v253, 7
	v_readlane_b32 s72, v253, 8
	v_readlane_b32 s73, v253, 9
	v_mov_b32_e32 v1, 0x358637bd
	s_nop 4

; #define PG8_BAR __builtin_amdgcn_s_barrier()
; template <class Epi, class Sched, bool ALIGN_EPI, int LMASK = -1, int LMASKB = LMASK>
; __device__ __forceinline__ void gemm_phase(PG8_LAS unsigned char* lds, const Gemm g, const Sched& S, const Epi& E) {
;     ...
;         if constexpr (ALIGN_EPI) { if (wr == 0) PG8_BAR; }
;         E(acc, cur, wr, wc, fr, fq);
;         if (!has_next) break;
; #pragma unroll
;         for (int a = 0; a < 2; ++a)
; #pragma unroll
;             for (int b = 0; b < 2; ++b)
; #pragma unroll
;                 for (int m = 0; m < 4; ++m)
; #pragma unroll
;                     for (int n = 0; n < 2; ++n) acc[a][b][m][n] = (f32x4){0.f, 0.f, 0.f, 0.f};
;         cur = nxt; cA = nA; cB = nB; ++ui;
;         if constexpr (ALIGN_EPI) { if (wr == 1) PG8_BAR; }
.LBB0_297:
	s_cmp_lg_u32 s71, 0
	s_cbranch_scc1 .Ldefer_skipM
	s_mov_b32 s100, 0x20180
	v_mov_b32_e32 v2, s100
	ds_read_b32 v3, v2 offset:4
	ds_read_b32 v4, v2
	ds_read_b32 v2, v2 offset:8
	s_load_dword s101, s[90:91], 0x0
	s_waitcnt lgkmcnt(0)
	v_readfirstlane_b32 s100, v2
	v_readfirstlane_b32 s98, v3
	v_readfirstlane_b32 s99, v4
	s_lshl_b32 s98, s98, 3
	s_add_i32 s98, s98, s99
	s_cmp_lg_u32 s100, 0
	s_cselect_b32 s100, s98, s77
	s_bfe_u32 s100, s100, 0x20001
	s_add_i32 s98, s100, 1
	s_cmp_eq_u32 s100, 0
	s_cselect_b32 s98, 0, s98
	s_cmp_eq_u32 s100, 3
	s_cselect_b32 s100, 5, s98
	s_cmpk_eq_i32 s101, 0x100
	s_cselect_b32 s100, s100, 0
	s_cmp_lg_u32 s100, s52
	s_cbranch_scc1 .Ldefer_skipM
	v_writelane_b32 v252, s0, 0
	v_writelane_b32 v252, s1, 1
	v_writelane_b32 v252, s2, 2
	v_writelane_b32 v252, s3, 3
	v_writelane_b32 v252, s4, 4
	v_writelane_b32 v252, s5, 5
	v_writelane_b32 v252, s6, 6
	v_writelane_b32 v252, s7, 7
	v_writelane_b32 v252, s8, 8
	v_writelane_b32 v252, s9, 9
	v_writelane_b32 v252, s10, 10
	v_writelane_b32 v252, s11, 11
	v_writelane_b32 v252, s12, 12
	v_writelane_b32 v252, s13, 13
	v_writelane_b32 v252, s14, 14
	v_writelane_b32 v252, s15, 15
	v_writelane_b32 v252, s16, 16
	v_writelane_b32 v252, s17, 17
	v_writelane_b32 v252, s18, 18
	v_writelane_b32 v252, s19, 19
	v_writelane_b32 v252, s20, 20
	v_writelane_b32 v252, s21, 21
	v_writelane_b32 v252, s22, 22
	v_writelane_b32 v252, s23, 23
	v_writelane_b32 v252, s24, 24
	v_writelane_b32 v252, s25, 25
	v_writelane_b32 v252, s26, 26
	v_writelane_b32 v252, s27, 27
	v_writelane_b32 v252, s28, 28
	v_writelane_b32 v252, s29, 29
	v_writelane_b32 v252, s30, 30
	v_writelane_b32 v252, s31, 31
	v_writelane_b32 v252, s32, 32
	v_writelane_b32 v252, s33, 33
	v_writelane_b32 v252, s34, 34
	v_writelane_b32 v252, s35, 35
	v_writelane_b32 v252, s36, 36
	v_writelane_b32 v252, s37, 37
	v_writelane_b32 v252, s38, 38
	v_writelane_b32 v252, s39, 39
	v_writelane_b32 v252, s40, 40
	v_writelane_b32 v252, s41, 41
	v_writelane_b32 v252, s42, 42
	v_writelane_b32 v252, s43, 43
	v_writelane_b32 v252, s44, 44
	v_writelane_b32 v252, s45, 45
	v_writelane_b32 v252, s46, 46
	v_writelane_b32 v252, s47, 47
	v_writelane_b32 v252, s48, 48
	v_writelane_b32 v252, s49, 49
	v_writelane_b32 v252, s50, 50
	v_writelane_b32 v252, s51, 51
	v_writelane_b32 v252, s52, 52
	v_writelane_b32 v252, s53, 53
	v_writelane_b32 v252, s54, 54
	v_writelane_b32 v252, s55, 55
	v_writelane_b32 v252, s56, 56
	v_writelane_b32 v252, s57, 57
	v_writelane_b32 v252, s58, 58
	v_writelane_b32 v252, s59, 59
	v_writelane_b32 v252, s60, 60
	v_writelane_b32 v252, s61, 61
	v_writelane_b32 v252, s62, 62
	v_writelane_b32 v252, s63, 63
	v_writelane_b32 v253, s64, 0
	v_writelane_b32 v253, s65, 1
	v_writelane_b32 v253, s66, 2
	v_writelane_b32 v253, s67, 3
	v_writelane_b32 v253, s68, 4
	v_writelane_b32 v253, s69, 5
	v_writelane_b32 v253, s70, 6
	v_writelane_b32 v253, s71, 7
	v_writelane_b32 v253, s72, 8
	v_writelane_b32 v253, s73, 9
	s_mov_b32 s101, 1
	s_branch .Lconv_shared

; #define SEAM(k) do { if (IN(k) && IN((k) + 1)) { XcdBarrier bar_; bar_.bar = (unsigned*)(kargs()->ws + WS_CTL) + CW_BAR; bar_.x = xb_xcc_id(); bar_.st = (volatile LAS unsigned*)(ldsp + MISC_OFF) + 8; xcd_barrier(bar_); } } while (0)
; __global__ void __launch_bounds__(NWAVES * 64, 2) fwd(Args args_unused) {
;     ...
;               pg8::gemm_phase<pg8::EpiProj, pg8::StaticOrder, true>(ldsp + RING_OFF, g, S, E); }
;             SEAM(pb);
.LBB0_300:
	s_cmp_lg_u32 s71, 0
	s_cbranch_scc1 .Ldefer_skipB
	s_mov_b32 s100, 0x20180
	v_mov_b32_e32 v2, s100
	ds_read_b32 v3, v2 offset:4
	ds_read_b32 v4, v2
	ds_read_b32 v2, v2 offset:8
	s_load_dword s101, s[90:91], 0x0
	s_waitcnt lgkmcnt(0)
	v_readfirstlane_b32 s100, v2
	v_readfirstlane_b32 s98, v3
	v_readfirstlane_b32 s99, v4
	s_lshl_b32 s98, s98, 3
	s_add_i32 s98, s98, s99
	s_cmp_lg_u32 s100, 0
	s_cselect_b32 s100, s98, s77
	s_bfe_u32 s100, s100, 0x20001
	s_add_i32 s98, s100, 1
	s_cmp_eq_u32 s100, 0
	s_cselect_b32 s98, 0, s98
	s_cmp_eq_u32 s100, 3
	s_cselect_b32 s100, 5, s98
	s_cmpk_eq_i32 s101, 0x100
	s_cselect_b32 s100, s100, 0
	s_cmp_lg_u32 s100, 5
	s_cbranch_scc1 .Ldefer_skipB
	v_writelane_b32 v252, s0, 0
	v_writelane_b32 v252, s1, 1
	v_writelane_b32 v252, s2, 2
	v_writelane_b32 v252, s3, 3
	v_writelane_b32 v252, s4, 4
	v_writelane_b32 v252, s5, 5
	v_writelane_b32 v252, s6, 6
	v_writelane_b32 v252, s7, 7
	v_writelane_b32 v252, s8, 8
	v_writelane_b32 v252, s9, 9
	v_writelane_b32 v252, s10, 10
	v_writelane_b32 v252, s11, 11
	v_writelane_b32 v252, s12, 12
	v_writelane_b32 v252, s13, 13
	v_writelane_b32 v252, s14, 14
	v_writelane_b32 v252, s15, 15
	v_writelane_b32 v252, s16, 16
	v_writelane_b32 v252, s17, 17
	v_writelane_b32 v252, s18, 18
	v_writelane_b32 v252, s19, 19
	v_writelane_b32 v252, s20, 20
	v_writelane_b32 v252, s21, 21
	v_writelane_b32 v252, s22, 22
	v_writelane_b32 v252, s23, 23
	v_writelane_b32 v252, s24, 24
	v_writelane_b32 v252, s25, 25
	v_writelane_b32 v252, s26, 26
	v_writelane_b32 v252, s27, 27
	v_writelane_b32 v252, s28, 28
	v_writelane_b32 v252, s29, 29
	v_writelane_b32 v252, s30, 30
	v_writelane_b32 v252, s31, 31
	v_writelane_b32 v252, s32, 32
	v_writelane_b32 v252, s33, 33
	v_writelane_b32 v252, s34, 34
	v_writelane_b32 v252, s35, 35
	v_writelane_b32 v252, s36, 36
	v_writelane_b32 v252, s37, 37
	v_writelane_b32 v252, s38, 38
	v_writelane_b32 v252, s39, 39
	v_writelane_b32 v252, s40, 40
	v_writelane_b32 v252, s41, 41
	v_writelane_b32 v252, s42, 42
	v_writelane_b32 v252, s43, 43
	v_writelane_b32 v252, s44, 44
	v_writelane_b32 v252, s45, 45
	v_writelane_b32 v252, s46, 46
	v_writelane_b32 v252, s47, 47
	v_writelane_b32 v252, s48, 48
	v_writelane_b32 v252, s49, 49
	v_writelane_b32 v252, s50, 50
	v_writelane_b32 v252, s51, 51
	v_writelane_b32 v252, s52, 52
	v_writelane_b32 v252, s53, 53
	v_writelane_b32 v252, s54, 54
	v_writelane_b32 v252, s55, 55
	v_writelane_b32 v252, s56, 56
	v_writelane_b32 v252, s57, 57
	v_writelane_b32 v252, s58, 58
	v_writelane_b32 v252, s59, 59
	v_writelane_b32 v252, s60, 60
	v_writelane_b32 v252, s61, 61
	v_writelane_b32 v252, s62, 62
	v_writelane_b32 v252, s63, 63
	v_writelane_b32 v253, s64, 0
	v_writelane_b32 v253, s65, 1
	v_writelane_b32 v253, s66, 2
	v_writelane_b32 v253, s67, 3
	v_writelane_b32 v253, s68, 4
	v_writelane_b32 v253, s69, 5
	v_writelane_b32 v253, s70, 6
	v_writelane_b32 v253, s71, 7
	v_writelane_b32 v253, s72, 8
	v_writelane_b32 v253, s73, 9
	s_mov_b32 s101, 2

; __device__ __forceinline__ unsigned cvt_pk_bf16(float lo, float hi) { f32x2 v = {lo, hi}; bf16x2_t b = __builtin_convertvector(v, bf16x2_t); return __builtin_bit_cast(unsigned, b); }
; #define LAS __attribute__((address_space(3)))
; template <int MODE, int K, int N>
; __device__ __forceinline__ void conv_blocked(const float* __restrict__ W, bf16* D, const float* __restrict__ gk, unsigned gtid, unsigned nthr, LAS unsigned char* scr  ) {
;     constexpr unsigned items = (unsigned)(K >> 5) * (unsigned)N;
;     const int lane = (int)(gtid & 63u);
;     for (unsigned it = gtid; it < items; it += nthr) {
;         const unsigned kb = it / (unsigned)N; const int n = (int)(it - kb * (unsigned)N), k0 = (int)kb * 32;
;         if (MODE == 1 && n >= C_U && n < C_GB) continue;
;         const float* src = W + (size_t)k0 * N + n;
;         float v[32];
; #pragma unroll
;         for (int i = 0; i < 32; ++i) v[i] = __builtin_nontemporal_load(src + (size_t)i * N);
;         if (gk) {
; #pragma unroll
;             for (int i = 0; i < 32; ++i) v[i] *= gk[k0 + i];
;         }
;         const int rho = pg8::p32inv(lane & 31), half = lane >> 5;
; #pragma unroll
;         for (int c = 0; c < 4; ++c) { v4u o; o.x = cvt_pk_bf16(v[8 * c], v[8 * c + 1]); o.y = cvt_pk_bf16(v[8 * c + 2], v[8 * c + 3]); o.z = cvt_pk_bf16(v[8 * c + 4], v[8 * c + 5]); o.w = cvt_pk_bf16(v[8 * c + 6], v[8 * c + 7]);
;             *(LAS v4u*)(scr + (half * 32 + rho) * 64 + ((c * 16) ^ ((rho & 8) << 2))) = o; }
; __device__ __forceinline__ void p0_prologue(const __attribute__((address_space(4))) Args* ka, unsigned char* ws, unsigned gtid, unsigned nthr, int gw, int ngw, int lane, LAS unsigned char* scr) {
;     ...
;     for (int l2 = 0; l2 < DEPTH * PROBE_P0; ++l2) { const int l = DEPTH - 1 - (l2 % DEPTH);
;         unsigned char* wl = ws + WS_W + (size_t)l * W_LAYER;
;         conv_blocked<0, DFF, DM>(in[11] + (size_t)l * DFF * DM, (bf16*)(wl + W_DN), nullptr, gtid, nthr, scr);
;         conv_blocked<0, DM, DFF>(in[10] + (size_t)l * DM * DFF, (bf16*)(wl + W_UP), in[4] + l * DM, gtid, nthr, scr);
;         conv_blocked<0, DM, DM>(in[2] + (size_t)l * DM * DM, (bf16*)(wl + W_OUT), nullptr, gtid, nthr, scr);
;         conv_blocked<1, DM, NIN>(in[1] + (size_t)l * DM * NIN, (bf16*)(wl + W_IN), in[3] + l * DM, gtid, nthr, scr);
.Lcs_33:
	s_or_b64 exec, exec, s[2:3]
	s_ashr_i32 s57, s46, 6
	s_lshl_b32 s2, s57, 12
	v_lshrrev_b32_e32 v4, 1, v1
	s_waitcnt lgkmcnt(0)
	s_mov_b32 s10, 0x1c200
	s_cmp_lt_u32 s57, 4
	s_cselect_b32 s10, 0xc000, s10
	s_add_i32 s10, s10, s2
	v_lshlrev_b32_e32 v3, 2, v1
	v_and_b32_e32 v4, 12, v4
	s_add_u32 s58, s24, 0x2000000
	v_and_b32_e32 v3, 16, v3
	v_and_or_b32 v4, v22, 3, v4
	v_and_b32_e32 v5, 32, v22
	s_addc_u32 s59, s25, 0
	v_or3_b32 v3, v5, v3, v4
	v_and_b32_e32 v2, 63, v22
	v_lshl_add_u32 v6, v3, 6, s10
	v_lshlrev_b32_e32 v3, 1, v1
	s_cmp_lg_u64 s[26:27], 0
	s_mov_b32 s2, 0x200000
	v_and_b32_e32 v8, 32, v3
	v_lshlrev_b32_e32 v4, 4, v2
	v_mov_b32_e32 v7, 0
	v_bitop3_b32 v9, v3, 32, v3 bitop3:0xc
	s_cselect_b64 s[30:31], -1, 0
	s_mov_b32 s60, 0x80000
	s_mov_b32 s61, 0x140000
	s_cmp_lg_u64 s[18:19], 0
	v_lshlrev_b32_e32 v3, 5, v22
	s_mov_b32 s29, 0
	v_cmp_gt_u32_e64 s[4:5], s2, v1
	s_mov_b32 s28, 1
	v_mov_b32_e32 v5, v7
	v_cmp_gt_u32_e64 s[6:7], s60, v1
	v_cmp_gt_u32_e64 s[8:9], s61, v1
	s_cselect_b64 s[34:35], -1, 0
	v_lshl_add_u32 v3, s33, 14, v3
	s_lshl_b32 s62, s1, 14
	v_sub_u32_e32 v44, 0, v2
	s_mov_b64 s[2:3], -1
	s_mov_b64 s[36:37], 0xf000000
	v_add_u32_e32 v45, v6, v8
	v_add_u32_e32 v46, v6, v9
	s_mov_b32 s63, 0x1fffff
	s_mov_b64 s[38:39], 0x7000000
	s_mov_b32 s64, 0xa0000
	s_mov_b32 s65, 0xf0000
	s_mov_b64 s[40:41], 0x5000000
	s_mov_b32 s66, 0x7ffff
	s_mov_b32 s67, 0xcccccccd
	s_movk_i32 s68, 0xd800
	s_movk_i32 s69, 0x3ff
	s_movk_i32 s70, 0x60
	s_mov_b32 s71, 0x13ffff
	v_add_u32_e32 v47, s10, v4
	v_mov_b32_e32 v48, 0x7c
	s_branch .Lcs_35

; template <int MODE, int K, int N>
; __device__ __forceinline__ void conv_blocked(const float* __restrict__ W, bf16* D, const float* __restrict__ gk, unsigned gtid, unsigned nthr, LAS unsigned char* scr  ) {
;     ...
;     for (unsigned it = gtid; it < items; it += nthr) {
;         const unsigned kb = it / (unsigned)N; const int n = (int)(it - kb * (unsigned)N), k0 = (int)kb * 32;
;         if (MODE == 1 && n >= C_U && n < C_GB) continue;
;         const float* src = W + (size_t)k0 * N + n;
;         float v[32];
; #pragma unroll
;         for (int i = 0; i < 32; ++i) v[i] = __builtin_nontemporal_load(src + (size_t)i * N);
.Lcs_35:
	s_mul_i32 s10, s28, 0x17000000
	s_add_u32 s10, s58, s10
	s_addc_u32 s11, s59, 0
	s_lshl_b64 s[44:45], s[28:29], 28
	v_lshl_add_u64 v[8:9], s[10:11], 0, v[4:5]
	s_and_saveexec_b64 s[10:11], s[4:5]
	s_cbranch_execz .Lcs_38
	s_add_u32 s42, s22, s44
	s_addc_u32 s43, s23, s45
	v_lshl_add_u64 v[10:11], v[8:9], 0, s[36:37]
	s_mov_b64 s[46:47], 0
	v_mov_b32_e32 v12, v3
	v_mov_b32_e32 v13, v1
	v_mov_b32_e32 v85, 0
.Lcs_37:
	v_and_b32_e32 v6, 0x3fe0000, v12
	v_and_b32_e32 v22, 0xfff, v13
	v_lshlrev_b32_e32 v6, 2, v6
	v_lshl_add_u64 v[14:15], s[42:43], 0, v[6:7]
	v_lshlrev_b32_e32 v6, 2, v22
	v_lshl_add_u64 v[14:15], v[14:15], 0, v[6:7]
	v_add_co_u32_e32 v16, vcc, 0x4000, v14
	global_load_dword v23, v[14:15], off nt
	s_nop 0
	v_addc_co_u32_e32 v17, vcc, 0, v15, vcc
	v_add_co_u32_e32 v18, vcc, 0x8000, v14
	global_load_dword v24, v[16:17], off nt
	s_nop 0
	v_addc_co_u32_e32 v19, vcc, 0, v15, vcc
	v_add_co_u32_e32 v16, vcc, 0xc000, v14
	v_lshrrev_b32_e32 v6, 2, v13
	s_nop 0
	v_addc_co_u32_e32 v17, vcc, 0, v15, vcc
	v_add_co_u32_e32 v20, vcc, 0x10000, v14
	global_load_dword v25, v[18:19], off nt
	global_load_dword v26, v[16:17], off nt
	v_addc_co_u32_e32 v21, vcc, 0, v15, vcc
	v_add_co_u32_e32 v16, vcc, 0x14000, v14
	v_and_b32_e32 v6, 0x7fc00, v6
	s_nop 0
	v_addc_co_u32_e32 v17, vcc, 0, v15, vcc
	v_add_co_u32_e32 v18, vcc, 0x18000, v14
	global_load_dword v27, v[20:21], off nt
	global_load_dword v28, v[16:17], off nt
	v_addc_co_u32_e32 v19, vcc, 0, v15, vcc
	v_add_co_u32_e32 v16, vcc, 0x1c000, v14
	v_lshl_add_u64 v[30:31], v[10:11], 0, v[6:7]
	s_nop 0
	v_addc_co_u32_e32 v17, vcc, 0, v15, vcc
	v_add_co_u32_e32 v20, vcc, 0x20000, v14
	global_load_dword v29, v[18:19], off nt
	global_load_dword v40, v[16:17], off nt
	v_addc_co_u32_e32 v21, vcc, 0, v15, vcc
	v_add_co_u32_e32 v16, vcc, 0x24000, v14
	v_add_u32_e32 v13, s0, v13
	s_nop 0
	v_addc_co_u32_e32 v17, vcc, 0, v15, vcc
	v_add_co_u32_e32 v18, vcc, 0x28000, v14
	global_load_dword v41, v[20:21], off nt
	global_load_dword v42, v[16:17], off nt
	v_addc_co_u32_e32 v19, vcc, 0, v15, vcc
	v_add_co_u32_e32 v16, vcc, 0x2c000, v14
	v_add_u32_e32 v12, s62, v12
	s_nop 0
	v_addc_co_u32_e32 v17, vcc, 0, v15, vcc
	v_add_co_u32_e32 v20, vcc, 0x30000, v14
	global_load_dword v43, v[18:19], off nt
	global_load_dword v49, v[16:17], off nt
	v_addc_co_u32_e32 v21, vcc, 0, v15, vcc
	v_add_co_u32_e32 v16, vcc, 0x34000, v14
	s_nop 1
	v_addc_co_u32_e32 v17, vcc, 0, v15, vcc
	v_add_co_u32_e32 v18, vcc, 0x38000, v14
	global_load_dword v50, v[20:21], off nt
	global_load_dword v51, v[16:17], off nt
	v_addc_co_u32_e32 v19, vcc, 0, v15, vcc
	v_add_co_u32_e32 v16, vcc, 0x3c000, v14
	s_nop 1
	v_addc_co_u32_e32 v17, vcc, 0, v15, vcc
	v_add_co_u32_e32 v20, vcc, 0x40000, v14
	global_load_dword v52, v[18:19], off nt
	global_load_dword v53, v[16:17], off nt
	v_addc_co_u32_e32 v21, vcc, 0, v15, vcc
	v_add_co_u32_e32 v16, vcc, 0x44000, v14
	s_nop 1
	v_addc_co_u32_e32 v17, vcc, 0, v15, vcc
	v_add_co_u32_e32 v18, vcc, 0x48000, v14
	global_load_dword v54, v[20:21], off nt
	global_load_dword v55, v[16:17], off nt
	v_addc_co_u32_e32 v19, vcc, 0, v15, vcc
	v_add_co_u32_e32 v16, vcc, 0x4c000, v14
	s_nop 1
	v_addc_co_u32_e32 v17, vcc, 0, v15, vcc
	v_add_co_u32_e32 v20, vcc, 0x50000, v14
	global_load_dword v56, v[18:19], off nt
	global_load_dword v57, v[16:17], off nt
	v_addc_co_u32_e32 v21, vcc, 0, v15, vcc
	v_add_co_u32_e32 v16, vcc, 0x54000, v14
	s_nop 1
	v_addc_co_u32_e32 v17, vcc, 0, v15, vcc
	v_add_co_u32_e32 v18, vcc, 0x58000, v14
	global_load_dword v58, v[20:21], off nt
	global_load_dword v59, v[16:17], off nt
	v_addc_co_u32_e32 v19, vcc, 0, v15, vcc
	v_add_co_u32_e32 v16, vcc, 0x5c000, v14
	s_nop 1
	v_addc_co_u32_e32 v17, vcc, 0, v15, vcc
	v_add_co_u32_e32 v20, vcc, 0x60000, v14
	global_load_dword v60, v[18:19], off nt
	global_load_dword v61, v[16:17], off nt
	v_addc_co_u32_e32 v21, vcc, 0, v15, vcc
	v_add_co_u32_e32 v16, vcc, 0x64000, v14
	s_nop 1
	v_addc_co_u32_e32 v17, vcc, 0, v15, vcc
	v_add_co_u32_e32 v18, vcc, 0x68000, v14
	global_load_dword v62, v[20:21], off nt
	global_load_dword v63, v[16:17], off nt
	v_addc_co_u32_e32 v19, vcc, 0, v15, vcc
	v_add_co_u32_e32 v16, vcc, 0x6c000, v14
	s_nop 1
	v_addc_co_u32_e32 v17, vcc, 0, v15, vcc
	v_add_co_u32_e32 v20, vcc, 0x70000, v14
	global_load_dword v64, v[18:19], off nt
	global_load_dword v65, v[16:17], off nt
	v_addc_co_u32_e32 v21, vcc, 0, v15, vcc
	v_add_co_u32_e32 v16, vcc, 0x74000, v14
	s_nop 1
	v_addc_co_u32_e32 v17, vcc, 0, v15, vcc
	v_add_co_u32_e32 v18, vcc, 0x78000, v14
	global_load_dword v66, v[20:21], off nt
	global_load_dword v67, v[16:17], off nt
	v_addc_co_u32_e32 v19, vcc, 0, v15, vcc
	v_add_co_u32_e32 v14, vcc, 0x7c000, v14
	s_nop 1
	v_addc_co_u32_e32 v15, vcc, 0, v15, vcc
	global_load_dword v68, v[18:19], off nt
	global_load_dword v69, v[14:15], off nt
	v_cmp_ge_u32_e32 vcc, s63, v13
	v_subrev_u32_e32 v86, s62, v12
	v_subrev_u32_e32 v87, s0, v13
	s_mov_b64 s[98:99], vcc
	v_cndmask_b32_e32 v86, v86, v12, vcc
	v_cndmask_b32_e32 v87, v87, v13, vcc
	v_add_u32_e32 v13, s0, v13
	v_add_u32_e32 v12, s62, v12
	v_and_b32_e32 v84, 0x3fe0000, v86
	v_and_b32_e32 v96, 0xfff, v87
	v_lshlrev_b32_e32 v84, 2, v84
	v_lshl_add_u64 v[88:89], s[42:43], 0, v[84:85]
	v_lshlrev_b32_e32 v84, 2, v96
	v_lshl_add_u64 v[88:89], v[88:89], 0, v[84:85]
	v_add_co_u32_e32 v90, vcc, 0x4000, v88
	global_load_dword v97, v[88:89], off nt
	s_nop 0
	v_addc_co_u32_e32 v91, vcc, 0, v89, vcc
	v_add_co_u32_e32 v92, vcc, 0x8000, v88
	global_load_dword v98, v[90:91], off nt
	s_nop 0
	v_addc_co_u32_e32 v93, vcc, 0, v89, vcc
	v_add_co_u32_e32 v90, vcc, 0xc000, v88
	v_lshrrev_b32_e32 v84, 2, v87
	s_nop 0
; __device__ __forceinline__ unsigned cvt_pk_bf16(float lo, float hi) { f32x2 v = {lo, hi}; bf16x2_t b = __builtin_convertvector(v, bf16x2_t); return __builtin_bit_cast(unsigned, b); }
; #define LAS __attribute__((address_space(3)))
; template <int MODE, int K, int N>
; __device__ __forceinline__ void conv_blocked(const float* __restrict__ W, bf16* D, const float* __restrict__ gk, unsigned gtid, unsigned nthr, LAS unsigned char* scr  ) {
;     ...
;     for (unsigned it = gtid; it < items; it += nthr) {
;         const unsigned kb = it / (unsigned)N; const int n = (int)(it - kb * (unsigned)N), k0 = (int)kb * 32;
;         if (MODE == 1 && n >= C_U && n < C_GB) continue;
;         const float* src = W + (size_t)k0 * N + n;
;         float v[32];
; #pragma unroll
;         for (int i = 0; i < 32; ++i) v[i] = __builtin_nontemporal_load(src + (size_t)i * N);
;         if (gk) {
; #pragma unroll
;             for (int i = 0; i < 32; ++i) v[i] *= gk[k0 + i];
;         }
;         const int rho = pg8::p32inv(lane & 31), half = lane >> 5;
; #pragma unroll
;         for (int c = 0; c < 4; ++c) { v4u o; o.x = cvt_pk_bf16(v[8 * c], v[8 * c + 1]); o.y = cvt_pk_bf16(v[8 * c + 2], v[8 * c + 3]); o.z = cvt_pk_bf16(v[8 * c + 4], v[8 * c + 5]); o.w = cvt_pk_bf16(v[8 * c + 6], v[8 * c + 7]);
;             *(LAS v4u*)(scr + (half * 32 + rho) * 64 + ((c * 16) ^ ((rho & 8) << 2))) = o; }
;         const int nb = n - lane;
; #pragma unroll
;         for (int i = 0; i < 4; ++i) { const int h2 = i >> 1, b2 = i & 1; const int gp = ((MODE == 1) ? nperm(nb + 32 * h2) : nb + 32 * h2) & ~31;
;             const v4u o = *(const LAS v4u*)(scr + (h2 * 32 + b2 * 16) * 64 + lane * 16);
;             *(v4u*)((unsigned char*)D + ((size_t)((gp >> 4) + b2) * (K >> 5) + (size_t)(k0 >> 5)) * 1024 + lane * 16) = o; }
	v_addc_co_u32_e32 v91, vcc, 0, v89, vcc
	v_add_co_u32_e32 v94, vcc, 0x10000, v88
	global_load_dword v99, v[92:93], off nt
	global_load_dword v100, v[90:91], off nt
	v_addc_co_u32_e32 v95, vcc, 0, v89, vcc
	v_add_co_u32_e32 v90, vcc, 0x14000, v88
	v_and_b32_e32 v84, 0x7fc00, v84
	s_nop 0
	v_addc_co_u32_e32 v91, vcc, 0, v89, vcc
	v_add_co_u32_e32 v92, vcc, 0x18000, v88
	global_load_dword v101, v[94:95], off nt
	global_load_dword v102, v[90:91], off nt
	v_addc_co_u32_e32 v93, vcc, 0, v89, vcc
	v_add_co_u32_e32 v90, vcc, 0x1c000, v88
	v_lshl_add_u64 v[104:105], v[10:11], 0, v[84:85]
	s_nop 0
	v_addc_co_u32_e32 v91, vcc, 0, v89, vcc
	v_add_co_u32_e32 v94, vcc, 0x20000, v88
	global_load_dword v103, v[92:93], off nt
	global_load_dword v114, v[90:91], off nt
	v_addc_co_u32_e32 v95, vcc, 0, v89, vcc
	v_add_co_u32_e32 v90, vcc, 0x24000, v88
	v_add_u32_e32 v87, s0, v87
	s_nop 0
	v_addc_co_u32_e32 v91, vcc, 0, v89, vcc
	v_add_co_u32_e32 v92, vcc, 0x28000, v88
	global_load_dword v115, v[94:95], off nt
	global_load_dword v116, v[90:91], off nt
	v_addc_co_u32_e32 v93, vcc, 0, v89, vcc
	v_add_co_u32_e32 v90, vcc, 0x2c000, v88
	v_add_u32_e32 v86, s62, v86
	s_nop 0
	v_addc_co_u32_e32 v91, vcc, 0, v89, vcc
	v_add_co_u32_e32 v94, vcc, 0x30000, v88
	global_load_dword v117, v[92:93], off nt
	global_load_dword v119, v[90:91], off nt
	v_addc_co_u32_e32 v95, vcc, 0, v89, vcc
	v_add_co_u32_e32 v90, vcc, 0x34000, v88
	s_nop 1
	v_addc_co_u32_e32 v91, vcc, 0, v89, vcc
	v_add_co_u32_e32 v92, vcc, 0x38000, v88
	global_load_dword v120, v[94:95], off nt
	global_load_dword v121, v[90:91], off nt
	v_addc_co_u32_e32 v93, vcc, 0, v89, vcc
	v_add_co_u32_e32 v90, vcc, 0x3c000, v88
	s_nop 1
	v_addc_co_u32_e32 v91, vcc, 0, v89, vcc
	v_add_co_u32_e32 v94, vcc, 0x40000, v88
	global_load_dword v122, v[92:93], off nt
	global_load_dword v123, v[90:91], off nt
	v_addc_co_u32_e32 v95, vcc, 0, v89, vcc
	v_add_co_u32_e32 v90, vcc, 0x44000, v88
	s_nop 1
	v_addc_co_u32_e32 v91, vcc, 0, v89, vcc
	v_add_co_u32_e32 v92, vcc, 0x48000, v88
	global_load_dword v124, v[94:95], off nt
	global_load_dword v125, v[90:91], off nt
	v_addc_co_u32_e32 v93, vcc, 0, v89, vcc
	v_add_co_u32_e32 v90, vcc, 0x4c000, v88
	s_nop 1
	v_addc_co_u32_e32 v91, vcc, 0, v89, vcc
	v_add_co_u32_e32 v94, vcc, 0x50000, v88
	global_load_dword v126, v[92:93], off nt
	global_load_dword v127, v[90:91], off nt
	v_addc_co_u32_e32 v95, vcc, 0, v89, vcc
	v_add_co_u32_e32 v90, vcc, 0x54000, v88
	s_nop 1
	v_addc_co_u32_e32 v91, vcc, 0, v89, vcc
	v_add_co_u32_e32 v92, vcc, 0x58000, v88
	global_load_dword v128, v[94:95], off nt
	global_load_dword v129, v[90:91], off nt
	v_addc_co_u32_e32 v93, vcc, 0, v89, vcc
	v_add_co_u32_e32 v90, vcc, 0x5c000, v88
	s_nop 1
	v_addc_co_u32_e32 v91, vcc, 0, v89, vcc
	v_add_co_u32_e32 v94, vcc, 0x60000, v88
	global_load_dword v130, v[92:93], off nt
	global_load_dword v131, v[90:91], off nt
	v_addc_co_u32_e32 v95, vcc, 0, v89, vcc
	v_add_co_u32_e32 v90, vcc, 0x64000, v88
	s_nop 1
	v_addc_co_u32_e32 v91, vcc, 0, v89, vcc
	v_add_co_u32_e32 v92, vcc, 0x68000, v88
	global_load_dword v132, v[94:95], off nt
	global_load_dword v133, v[90:91], off nt
	v_addc_co_u32_e32 v93, vcc, 0, v89, vcc
	v_add_co_u32_e32 v90, vcc, 0x6c000, v88
	s_nop 1
	v_addc_co_u32_e32 v91, vcc, 0, v89, vcc
	v_add_co_u32_e32 v94, vcc, 0x70000, v88
	global_load_dword v134, v[92:93], off nt
	global_load_dword v135, v[90:91], off nt
	v_addc_co_u32_e32 v95, vcc, 0, v89, vcc
	v_add_co_u32_e32 v90, vcc, 0x74000, v88
	s_nop 1
	v_addc_co_u32_e32 v91, vcc, 0, v89, vcc
	v_add_co_u32_e32 v92, vcc, 0x78000, v88
	s_waitcnt vmcnt(59)
	global_load_dword v136, v[94:95], off nt
	global_load_dword v137, v[90:91], off nt
	v_addc_co_u32_e32 v93, vcc, 0, v89, vcc
	v_add_co_u32_e32 v88, vcc, 0x7c000, v88
	s_nop 1
	v_addc_co_u32_e32 v89, vcc, 0, v89, vcc
	global_load_dword v138, v[92:93], off nt
	global_load_dword v139, v[88:89], off nt
	v_sub_u32_e32 v14, v22, v2
	v_ashrrev_i32_e32 v15, 4, v14
	v_add_u32_e32 v17, 32, v14
	v_and_b32_e32 v14, -2, v15
	v_ashrrev_i32_e32 v19, 4, v17
	v_or_b32_e32 v16, 1, v15
	v_ashrrev_i32_e32 v15, 31, v14
	v_and_b32_e32 v18, -2, v19
	v_ashrrev_i32_e32 v17, 31, v16
	v_or_b32_e32 v20, 1, v19
	v_lshlrev_b64 v[14:15], 19, v[14:15]
	v_ashrrev_i32_e32 v19, 31, v18
	v_lshlrev_b64 v[16:17], 19, v[16:17]
	v_lshl_add_u64 v[32:33], v[30:31], 0, v[14:15]
	v_lshlrev_b64 v[14:15], 19, v[18:19]
	v_lshl_add_u64 v[34:35], v[30:31], 0, v[16:17]
	v_lshl_add_u64 v[38:39], v[30:31], 0, v[14:15]
	s_waitcnt vmcnt(62)
; __device__ __forceinline__ unsigned cvt_pk_bf16(float lo, float hi) { f32x2 v = {lo, hi}; bf16x2_t b = __builtin_convertvector(v, bf16x2_t); return __builtin_bit_cast(unsigned, b); }
; #define LAS __attribute__((address_space(3)))
; template <int MODE, int K, int N>
; __device__ __forceinline__ void conv_blocked(const float* __restrict__ W, bf16* D, const float* __restrict__ gk, unsigned gtid, unsigned nthr, LAS unsigned char* scr  ) {
;     ...
;         const int rho = pg8::p32inv(lane & 31), half = lane >> 5;
; #pragma unroll
;         for (int c = 0; c < 4; ++c) { v4u o; o.x = cvt_pk_bf16(v[8 * c], v[8 * c + 1]); o.y = cvt_pk_bf16(v[8 * c + 2], v[8 * c + 3]); o.z = cvt_pk_bf16(v[8 * c + 4], v[8 * c + 5]); o.w = cvt_pk_bf16(v[8 * c + 6], v[8 * c + 7]);
;             *(LAS v4u*)(scr + (half * 32 + rho) * 64 + ((c * 16) ^ ((rho & 8) << 2))) = o; }
;         const int nb = n - lane;
; #pragma unroll
;         for (int i = 0; i < 4; ++i) { const int h2 = i >> 1, b2 = i & 1; const int gp = ((MODE == 1) ? nperm(nb + 32 * h2) : nb + 32 * h2) & ~31;
;             const v4u o = *(const LAS v4u*)(scr + (h2 * 32 + b2 * 16) * 64 + lane * 16);
;             *(v4u*)((unsigned char*)D + ((size_t)((gp >> 4) + b2) * (K >> 5) + (size_t)(k0 >> 5)) * 1024 + lane * 16) = o; }
;         asm volatile("s_waitcnt lgkmcnt(0)" ::: "memory");
	v_cvt_pk_bf16_f32 v14, v23, v24
	s_waitcnt vmcnt(60)
	v_cvt_pk_bf16_f32 v15, v25, v26
	s_waitcnt vmcnt(58)
	v_cvt_pk_bf16_f32 v16, v27, v28
	s_waitcnt vmcnt(56)
	v_cvt_pk_bf16_f32 v17, v29, v40
	ds_write_b128 v45, v[14:17]
	s_waitcnt vmcnt(54)
	v_cvt_pk_bf16_f32 v14, v41, v42
	s_waitcnt vmcnt(52)
	v_cvt_pk_bf16_f32 v15, v43, v49
	s_waitcnt vmcnt(50)
	v_cvt_pk_bf16_f32 v16, v50, v51
	s_waitcnt vmcnt(48)
	v_cvt_pk_bf16_f32 v17, v52, v53
	ds_write_b128 v45, v[14:17] offset:16
	s_waitcnt vmcnt(46)
	v_cvt_pk_bf16_f32 v14, v54, v55
	s_waitcnt vmcnt(44)
	v_cvt_pk_bf16_f32 v15, v56, v57
	v_ashrrev_i32_e32 v21, 31, v20
	v_lshlrev_b64 v[36:37], 19, v[20:21]
	s_waitcnt vmcnt(42)
	v_cvt_pk_bf16_f32 v16, v58, v59
	v_lshl_add_u64 v[30:31], v[30:31], 0, v[36:37]
	s_waitcnt vmcnt(40)
	v_cvt_pk_bf16_f32 v17, v60, v61
	ds_write_b128 v46, v[14:17]
	s_waitcnt vmcnt(38)
	v_cvt_pk_bf16_f32 v14, v62, v63
	s_waitcnt vmcnt(36)
	v_cvt_pk_bf16_f32 v15, v64, v65
	s_waitcnt vmcnt(34)
	v_cvt_pk_bf16_f32 v16, v66, v67
	s_waitcnt vmcnt(32)
	v_cvt_pk_bf16_f32 v17, v68, v69
	ds_write_b128 v46, v[14:17] offset:16
	ds_read_b128 v[14:17], v47
	ds_read_b128 v[18:21], v47 offset:1024
	ds_read_b128 v[22:25], v47 offset:2048
	ds_read_b128 v[26:29], v47 offset:3072
	s_waitcnt lgkmcnt(3)
	global_store_dwordx4 v[32:33], v[14:17], off
	s_waitcnt lgkmcnt(2)
	global_store_dwordx4 v[34:35], v[18:21], off
	s_waitcnt lgkmcnt(1)
	global_store_dwordx4 v[38:39], v[22:25], off
	s_waitcnt lgkmcnt(0)
	global_store_dwordx4 v[30:31], v[26:29], off
	s_waitcnt lgkmcnt(0)
	v_sub_u32_e32 v88, v96, v2
	v_ashrrev_i32_e32 v89, 4, v88
	v_add_u32_e32 v91, 32, v88
	v_and_b32_e32 v88, -2, v89
	v_ashrrev_i32_e32 v93, 4, v91
	v_or_b32_e32 v90, 1, v89
	v_ashrrev_i32_e32 v89, 31, v88
	v_and_b32_e32 v92, -2, v93
	v_ashrrev_i32_e32 v91, 31, v90
	v_or_b32_e32 v94, 1, v93
	v_lshlrev_b64 v[88:89], 19, v[88:89]
	v_ashrrev_i32_e32 v93, 31, v92
	v_lshlrev_b64 v[90:91], 19, v[90:91]
	v_lshl_add_u64 v[106:107], v[104:105], 0, v[88:89]
	v_lshlrev_b64 v[88:89], 19, v[92:93]
	v_lshl_add_u64 v[108:109], v[104:105], 0, v[90:91]
	v_lshl_add_u64 v[112:113], v[104:105], 0, v[88:89]
	s_waitcnt vmcnt(30)
	v_cvt_pk_bf16_f32 v88, v97, v98
	s_waitcnt vmcnt(28)
	v_cvt_pk_bf16_f32 v89, v99, v100
	s_waitcnt vmcnt(26)
	v_cvt_pk_bf16_f32 v90, v101, v102
	s_waitcnt vmcnt(24)
	v_cvt_pk_bf16_f32 v91, v103, v114
	ds_write_b128 v45, v[88:91]
	s_waitcnt vmcnt(22)
	v_cvt_pk_bf16_f32 v88, v115, v116
	s_waitcnt vmcnt(20)
	v_cvt_pk_bf16_f32 v89, v117, v119
	s_waitcnt vmcnt(18)
	v_cvt_pk_bf16_f32 v90, v120, v121
	s_waitcnt vmcnt(16)
	v_cvt_pk_bf16_f32 v91, v122, v123
	ds_write_b128 v45, v[88:91] offset:16
	s_waitcnt vmcnt(14)
	v_cvt_pk_bf16_f32 v88, v124, v125
	s_waitcnt vmcnt(12)
	v_cvt_pk_bf16_f32 v89, v126, v127
	v_ashrrev_i32_e32 v95, 31, v94
	v_lshlrev_b64 v[110:111], 19, v[94:95]
	s_waitcnt vmcnt(10)
	v_cvt_pk_bf16_f32 v90, v128, v129
	v_lshl_add_u64 v[104:105], v[104:105], 0, v[110:111]
	v_cmp_lt_u32_e32 vcc, s63, v87
	s_or_b64 s[46:47], vcc, s[46:47]
	s_waitcnt vmcnt(8)
	v_cvt_pk_bf16_f32 v91, v130, v131
	ds_write_b128 v46, v[88:91]
	s_waitcnt vmcnt(6)
	v_cvt_pk_bf16_f32 v88, v132, v133
	s_waitcnt vmcnt(4)
	v_cvt_pk_bf16_f32 v89, v134, v135
	s_waitcnt vmcnt(2)
	v_cvt_pk_bf16_f32 v90, v136, v137
	s_waitcnt vmcnt(0)
	v_cvt_pk_bf16_f32 v91, v138, v139
	ds_write_b128 v46, v[88:91] offset:16
	ds_read_b128 v[88:91], v47
	ds_read_b128 v[92:95], v47 offset:1024
	ds_read_b128 v[96:99], v47 offset:2048
	ds_read_b128 v[100:103], v47 offset:3072
	s_and_saveexec_b64 s[96:97], s[98:99]
	s_waitcnt lgkmcnt(3)
	global_store_dwordx4 v[106:107], v[88:91], off
	s_waitcnt lgkmcnt(2)
	global_store_dwordx4 v[108:109], v[92:95], off
	s_waitcnt lgkmcnt(1)
	global_store_dwordx4 v[112:113], v[96:99], off
	s_waitcnt lgkmcnt(0)
	global_store_dwordx4 v[104:105], v[100:103], off
	s_mov_b64 exec, s[96:97]
	s_waitcnt lgkmcnt(0)
	s_andn2_b64 exec, exec, s[46:47]
	s_cbranch_execnz .Lcs_37

; template <int MODE, int K, int N>
; __device__ __forceinline__ void conv_blocked(const float* __restrict__ W, bf16* D, const float* __restrict__ gk, unsigned gtid, unsigned nthr, LAS unsigned char* scr  ) {
;     ...
;     for (unsigned it = gtid; it < items; it += nthr) {
;         const unsigned kb = it / (unsigned)N; const int n = (int)(it - kb * (unsigned)N), k0 = (int)kb * 32;
;         if (MODE == 1 && n >= C_U && n < C_GB) continue;
;         const float* src = W + (size_t)k0 * N + n;
;         float v[32];
; #pragma unroll
;         for (int i = 0; i < 32; ++i) v[i] = __builtin_nontemporal_load(src + (size_t)i * N);
.Lcs_41:
	v_lshrrev_b32_e32 v51, 9, v49
	v_and_b32_e32 v52, 0xfe0, v51
	v_and_b32_e32 v50, 0x3fff, v49
	v_lshlrev_b32_e32 v6, 16, v52
	v_lshl_add_u64 v[12:13], s[44:45], 0, v[6:7]
	v_lshlrev_b32_e32 v6, 2, v50
	v_lshl_add_u64 v[36:37], v[12:13], 0, v[6:7]
	v_add_co_u32_e32 v14, vcc, 0x10000, v36
	s_nop 1
	v_addc_co_u32_e32 v15, vcc, 0, v37, vcc
	v_add_co_u32_e32 v16, vcc, 0x20000, v36
	s_nop 1
	v_addc_co_u32_e32 v17, vcc, 0, v37, vcc
	v_add_co_u32_e32 v18, vcc, 0x30000, v36
	s_nop 1
	v_addc_co_u32_e32 v19, vcc, 0, v37, vcc
	v_add_co_u32_e32 v20, vcc, 0x40000, v36
	s_nop 1
	v_addc_co_u32_e32 v21, vcc, 0, v37, vcc
	v_add_co_u32_e32 v22, vcc, 0x50000, v36
	s_nop 1
	v_addc_co_u32_e32 v23, vcc, 0, v37, vcc
	v_add_co_u32_e32 v24, vcc, 0x60000, v36
	s_nop 1
	v_addc_co_u32_e32 v25, vcc, 0, v37, vcc
	v_add_co_u32_e32 v26, vcc, 0x70000, v36
	s_nop 1
	v_addc_co_u32_e32 v27, vcc, 0, v37, vcc
	global_load_dword v12, v[36:37], off nt
	global_load_dword v13, v[14:15], off nt
	s_nop 0
	global_load_dword v14, v[16:17], off nt
	global_load_dword v15, v[18:19], off nt
	s_nop 0
	global_load_dword v16, v[20:21], off nt
	global_load_dword v17, v[22:23], off nt
	global_load_dword v18, v[24:25], off nt
	global_load_dword v19, v[26:27], off nt
	v_add_co_u32_e32 v20, vcc, s60, v36
	s_nop 1
	v_addc_co_u32_e32 v21, vcc, 0, v37, vcc
	v_add_co_u32_e32 v22, vcc, 0x90000, v36
	s_nop 1
	v_addc_co_u32_e32 v23, vcc, 0, v37, vcc
	v_add_co_u32_e32 v24, vcc, 0xa0000, v36
	s_nop 1
	v_addc_co_u32_e32 v25, vcc, 0, v37, vcc
	v_add_co_u32_e32 v26, vcc, 0xb0000, v36
	s_nop 1
	v_addc_co_u32_e32 v27, vcc, 0, v37, vcc
	v_add_co_u32_e32 v28, vcc, 0xc0000, v36
	s_nop 1
	v_addc_co_u32_e32 v29, vcc, 0, v37, vcc
	v_add_co_u32_e32 v30, vcc, 0xd0000, v36
	s_nop 1
	v_addc_co_u32_e32 v31, vcc, 0, v37, vcc
	v_add_co_u32_e32 v32, vcc, 0xe0000, v36
	s_nop 1
	v_addc_co_u32_e32 v33, vcc, 0, v37, vcc
	v_add_co_u32_e32 v34, vcc, 0xf0000, v36
	s_nop 1
	v_addc_co_u32_e32 v35, vcc, 0, v37, vcc
	global_load_dword v20, v[20:21], off nt
	s_nop 0
	global_load_dword v21, v[22:23], off nt
	s_nop 0
	global_load_dword v22, v[24:25], off nt
	global_load_dword v23, v[26:27], off nt
	s_nop 0
	global_load_dword v24, v[28:29], off nt
	global_load_dword v25, v[30:31], off nt
	global_load_dword v26, v[32:33], off nt
	global_load_dword v27, v[34:35], off nt
	v_add_co_u32_e32 v28, vcc, 0x100000, v36
	s_nop 1
	v_addc_co_u32_e32 v29, vcc, 0, v37, vcc
	v_add_co_u32_e32 v30, vcc, 0x110000, v36
	s_nop 1
	v_addc_co_u32_e32 v31, vcc, 0, v37, vcc
	v_add_co_u32_e32 v32, vcc, 0x120000, v36
	s_nop 1
	v_addc_co_u32_e32 v33, vcc, 0, v37, vcc
	v_add_co_u32_e32 v34, vcc, 0x130000, v36
	s_nop 1
	v_addc_co_u32_e32 v35, vcc, 0, v37, vcc
	v_add_co_u32_e32 v38, vcc, s61, v36
	s_nop 1
	v_addc_co_u32_e32 v39, vcc, 0, v37, vcc
	v_add_co_u32_e32 v40, vcc, 0x150000, v36
	s_nop 1
	v_addc_co_u32_e32 v41, vcc, 0, v37, vcc
	v_add_co_u32_e32 v42, vcc, 0x160000, v36
	s_nop 1
	v_addc_co_u32_e32 v43, vcc, 0, v37, vcc
	v_add_co_u32_e32 v54, vcc, 0x170000, v36
	s_nop 1
	v_addc_co_u32_e32 v55, vcc, 0, v37, vcc
	global_load_dword v28, v[28:29], off nt
	s_nop 0
	global_load_dword v29, v[30:31], off nt
	s_nop 0
	global_load_dword v30, v[32:33], off nt
	global_load_dword v31, v[34:35], off nt
	s_nop 0
	global_load_dword v32, v[38:39], off nt
	global_load_dword v33, v[40:41], off nt
	global_load_dword v34, v[42:43], off nt
	global_load_dword v35, v[54:55], off nt
	v_add_co_u32_e32 v38, vcc, 0x180000, v36
	s_nop 1
	v_addc_co_u32_e32 v39, vcc, 0, v37, vcc
	v_add_co_u32_e32 v40, vcc, 0x190000, v36
	s_nop 1
	v_addc_co_u32_e32 v41, vcc, 0, v37, vcc
	v_add_co_u32_e32 v42, vcc, 0x1a0000, v36
	s_nop 1
	v_addc_co_u32_e32 v43, vcc, 0, v37, vcc
	v_add_co_u32_e32 v54, vcc, 0x1b0000, v36
	s_nop 1
	v_addc_co_u32_e32 v55, vcc, 0, v37, vcc
	v_add_co_u32_e32 v56, vcc, 0x1c0000, v36
	s_nop 1
	v_addc_co_u32_e32 v57, vcc, 0, v37, vcc
	v_add_co_u32_e32 v58, vcc, 0x1d0000, v36
	s_nop 1
	v_addc_co_u32_e32 v59, vcc, 0, v37, vcc
	v_add_co_u32_e32 v60, vcc, 0x1e0000, v36
	s_nop 1
	v_addc_co_u32_e32 v61, vcc, 0, v37, vcc
	v_add_co_u32_e32 v62, vcc, 0x1f0000, v36
	s_nop 1
	v_addc_co_u32_e32 v63, vcc, 0, v37, vcc
	global_load_dword v36, v[38:39], off nt
	global_load_dword v37, v[40:41], off nt
	s_nop 0
	global_load_dword v38, v[42:43], off nt
	global_load_dword v39, v[54:55], off nt
	s_nop 0
	global_load_dword v42, v[56:57], off nt
	global_load_dword v43, v[58:59], off nt
	global_load_dword v40, v[60:61], off nt
	global_load_dword v41, v[62:63], off nt
	v_add_u32_e32 v119, s0, v49
	v_cmp_ge_u32_e32 vcc, s63, v119
	v_mov_b32_e32 v85, 0
	s_nop 0
	v_cndmask_b32_e32 v119, v49, v119, vcc
	s_mov_b64 s[98:99], vcc
	v_lshrrev_b32_e32 v121, 9, v119
	v_and_b32_e32 v122, 0xfe0, v121
	v_and_b32_e32 v120, 0x3fff, v119
	v_lshlrev_b32_e32 v84, 16, v122
	v_lshl_add_u64 v[86:87], s[44:45], 0, v[84:85]
	v_lshlrev_b32_e32 v84, 2, v120
	v_lshl_add_u64 v[110:111], v[86:87], 0, v[84:85]
	v_add_co_u32_e32 v88, vcc, 0x10000, v110
	s_nop 1
	v_addc_co_u32_e32 v89, vcc, 0, v111, vcc
	v_add_co_u32_e32 v90, vcc, 0x20000, v110
	s_nop 1
	v_addc_co_u32_e32 v91, vcc, 0, v111, vcc
	v_add_co_u32_e32 v92, vcc, 0x30000, v110
	s_nop 1
	v_addc_co_u32_e32 v93, vcc, 0, v111, vcc
	v_add_co_u32_e32 v94, vcc, 0x40000, v110
	s_nop 1
	v_addc_co_u32_e32 v95, vcc, 0, v111, vcc
	v_add_co_u32_e32 v96, vcc, 0x50000, v110
	s_nop 1
	v_addc_co_u32_e32 v97, vcc, 0, v111, vcc
	v_add_co_u32_e32 v98, vcc, 0x60000, v110
	s_nop 1
	v_addc_co_u32_e32 v99, vcc, 0, v111, vcc
	v_add_co_u32_e32 v100, vcc, 0x70000, v110
	s_nop 1
	v_addc_co_u32_e32 v101, vcc, 0, v111, vcc
	global_load_dword v86, v[110:111], off nt
	global_load_dword v87, v[88:89], off nt
; template <int MODE, int K, int N>
; __device__ __forceinline__ void conv_blocked(const float* __restrict__ W, bf16* D, const float* __restrict__ gk, unsigned gtid, unsigned nthr, LAS unsigned char* scr  ) {
;     ...
;         for (int i = 0; i < 32; ++i) v[i] = __builtin_nontemporal_load(src + (size_t)i * N);
;         if (gk) {
; #pragma unroll
;             for (int i = 0; i < 32; ++i) v[i] *= gk[k0 + i];
;         }
	s_nop 0
	global_load_dword v88, v[90:91], off nt
	global_load_dword v89, v[92:93], off nt
	s_nop 0
	global_load_dword v90, v[94:95], off nt
	global_load_dword v91, v[96:97], off nt
	global_load_dword v92, v[98:99], off nt
	global_load_dword v93, v[100:101], off nt
	v_add_co_u32_e32 v94, vcc, s60, v110
	s_nop 1
	v_addc_co_u32_e32 v95, vcc, 0, v111, vcc
	v_add_co_u32_e32 v96, vcc, 0x90000, v110
	s_nop 1
	v_addc_co_u32_e32 v97, vcc, 0, v111, vcc
	v_add_co_u32_e32 v98, vcc, 0xa0000, v110
	s_nop 1
	v_addc_co_u32_e32 v99, vcc, 0, v111, vcc
	v_add_co_u32_e32 v100, vcc, 0xb0000, v110
	s_nop 1
	v_addc_co_u32_e32 v101, vcc, 0, v111, vcc
	v_add_co_u32_e32 v102, vcc, 0xc0000, v110
	s_nop 1
	v_addc_co_u32_e32 v103, vcc, 0, v111, vcc
	v_add_co_u32_e32 v104, vcc, 0xd0000, v110
	s_nop 1
	v_addc_co_u32_e32 v105, vcc, 0, v111, vcc
	v_add_co_u32_e32 v106, vcc, 0xe0000, v110
	s_nop 1
	v_addc_co_u32_e32 v107, vcc, 0, v111, vcc
	v_add_co_u32_e32 v108, vcc, 0xf0000, v110
	s_nop 1
	v_addc_co_u32_e32 v109, vcc, 0, v111, vcc
	global_load_dword v94, v[94:95], off nt
	s_nop 0
	global_load_dword v95, v[96:97], off nt
	s_nop 0
	global_load_dword v96, v[98:99], off nt
	global_load_dword v97, v[100:101], off nt
	s_nop 0
	global_load_dword v98, v[102:103], off nt
	global_load_dword v99, v[104:105], off nt
	global_load_dword v100, v[106:107], off nt
	global_load_dword v101, v[108:109], off nt
	v_add_co_u32_e32 v102, vcc, 0x100000, v110
	s_nop 1
	v_addc_co_u32_e32 v103, vcc, 0, v111, vcc
	v_add_co_u32_e32 v104, vcc, 0x110000, v110
	s_nop 1
	v_addc_co_u32_e32 v105, vcc, 0, v111, vcc
	v_add_co_u32_e32 v106, vcc, 0x120000, v110
	s_nop 1
	v_addc_co_u32_e32 v107, vcc, 0, v111, vcc
	v_add_co_u32_e32 v108, vcc, 0x130000, v110
	s_nop 1
	v_addc_co_u32_e32 v109, vcc, 0, v111, vcc
	v_add_co_u32_e32 v112, vcc, s61, v110
	s_nop 1
	v_addc_co_u32_e32 v113, vcc, 0, v111, vcc
	v_add_co_u32_e32 v114, vcc, 0x150000, v110
	s_nop 1
	v_addc_co_u32_e32 v115, vcc, 0, v111, vcc
	v_add_co_u32_e32 v116, vcc, 0x160000, v110
	s_nop 1
	v_addc_co_u32_e32 v117, vcc, 0, v111, vcc
	v_add_co_u32_e32 v124, vcc, 0x170000, v110
	s_nop 1
	v_addc_co_u32_e32 v125, vcc, 0, v111, vcc
	global_load_dword v102, v[102:103], off nt
	s_nop 0
	global_load_dword v103, v[104:105], off nt
	s_nop 0
	global_load_dword v104, v[106:107], off nt
	global_load_dword v105, v[108:109], off nt
	s_nop 0
	global_load_dword v106, v[112:113], off nt
	global_load_dword v107, v[114:115], off nt
	global_load_dword v108, v[116:117], off nt
	global_load_dword v109, v[124:125], off nt
	v_add_co_u32_e32 v112, vcc, 0x180000, v110
	s_nop 1
	v_addc_co_u32_e32 v113, vcc, 0, v111, vcc
	v_add_co_u32_e32 v114, vcc, 0x190000, v110
	s_nop 1
	v_addc_co_u32_e32 v115, vcc, 0, v111, vcc
	v_add_co_u32_e32 v116, vcc, 0x1a0000, v110
	s_nop 1
	v_addc_co_u32_e32 v117, vcc, 0, v111, vcc
	v_add_co_u32_e32 v124, vcc, 0x1b0000, v110
	s_nop 1
	v_addc_co_u32_e32 v125, vcc, 0, v111, vcc
	v_add_co_u32_e32 v126, vcc, 0x1c0000, v110
	s_nop 1
	v_addc_co_u32_e32 v127, vcc, 0, v111, vcc
	v_add_co_u32_e32 v128, vcc, 0x1d0000, v110
	s_nop 1
	v_addc_co_u32_e32 v129, vcc, 0, v111, vcc
	v_add_co_u32_e32 v130, vcc, 0x1e0000, v110
	s_nop 1
	v_addc_co_u32_e32 v131, vcc, 0, v111, vcc
	v_add_co_u32_e32 v132, vcc, 0x1f0000, v110
	s_nop 1
	v_addc_co_u32_e32 v133, vcc, 0, v111, vcc
	global_load_dword v110, v[112:113], off nt
	global_load_dword v111, v[114:115], off nt
	s_nop 0
	global_load_dword v112, v[116:117], off nt
	global_load_dword v113, v[124:125], off nt
	s_nop 0
	s_waitcnt vmcnt(59)
	global_load_dword v116, v[126:127], off nt
	global_load_dword v117, v[128:129], off nt
	global_load_dword v114, v[130:131], off nt
	global_load_dword v115, v[132:133], off nt
	s_andn2_b64 vcc, exec, s[30:31]
	s_cbranch_vccnz .Lcs_40
	s_waitcnt vmcnt(54)
	v_lshlrev_b32_e32 v6, 2, v52
	global_load_dwordx3 v[80:82], v6, s[46:47] offset:112
	global_load_dwordx4 v[52:55], v6, s[46:47]
	global_load_dwordx4 v[56:59], v6, s[46:47] offset:16
	global_load_dwordx4 v[60:63], v6, s[46:47] offset:32
	global_load_dwordx4 v[64:67], v6, s[46:47] offset:48
	global_load_dwordx4 v[68:71], v6, s[46:47] offset:64
	global_load_dwordx4 v[72:75], v6, s[46:47] offset:80
	global_load_dwordx4 v[76:79], v6, s[46:47] offset:96
	v_lshl_or_b32 v6, v51, 2, v48
	global_load_dword v83, v6, s[46:47]
	s_waitcnt vmcnt(8)
	v_pk_mul_f32 v[42:43], v[42:43], v[80:81]
	s_waitcnt vmcnt(7)
	v_pk_mul_f32 v[12:13], v[12:13], v[52:53]
	v_pk_mul_f32 v[14:15], v[14:15], v[54:55]
	s_waitcnt vmcnt(6)
	v_pk_mul_f32 v[16:17], v[16:17], v[56:57]
	v_pk_mul_f32 v[18:19], v[18:19], v[58:59]
	s_waitcnt vmcnt(5)
	v_pk_mul_f32 v[20:21], v[20:21], v[60:61]
	v_pk_mul_f32 v[22:23], v[22:23], v[62:63]
	s_waitcnt vmcnt(4)
	v_pk_mul_f32 v[24:25], v[24:25], v[64:65]
	v_pk_mul_f32 v[26:27], v[26:27], v[66:67]
	s_waitcnt vmcnt(3)
	v_pk_mul_f32 v[28:29], v[28:29], v[68:69]
	v_pk_mul_f32 v[30:31], v[30:31], v[70:71]
	s_waitcnt vmcnt(2)
	v_pk_mul_f32 v[32:33], v[32:33], v[72:73]
	v_pk_mul_f32 v[34:35], v[34:35], v[74:75]
	s_waitcnt vmcnt(1)
	v_pk_mul_f32 v[36:37], v[36:37], v[76:77]
	v_pk_mul_f32 v[38:39], v[38:39], v[78:79]
	s_waitcnt vmcnt(0)
	v_pk_mul_f32 v[40:41], v[40:41], v[82:83]
	v_lshlrev_b32_e32 v6, 2, v122
	global_load_dwordx3 v[80:82], v6, s[46:47] offset:112
	global_load_dwordx4 v[52:55], v6, s[46:47]
	global_load_dwordx4 v[56:59], v6, s[46:47] offset:16
	global_load_dwordx4 v[60:63], v6, s[46:47] offset:32
	global_load_dwordx4 v[64:67], v6, s[46:47] offset:48
	global_load_dwordx4 v[68:71], v6, s[46:47] offset:64
	global_load_dwordx4 v[72:75], v6, s[46:47] offset:80
	global_load_dwordx4 v[76:79], v6, s[46:47] offset:96
	v_lshl_or_b32 v6, v121, 2, v48
	global_load_dword v83, v6, s[46:47]
	s_waitcnt vmcnt(8)
	v_pk_mul_f32 v[116:117], v[116:117], v[80:81]
	s_waitcnt vmcnt(7)
	v_pk_mul_f32 v[86:87], v[86:87], v[52:53]
	v_pk_mul_f32 v[88:89], v[88:89], v[54:55]
	s_waitcnt vmcnt(6)
	v_pk_mul_f32 v[90:91], v[90:91], v[56:57]
	v_pk_mul_f32 v[92:93], v[92:93], v[58:59]
	s_waitcnt vmcnt(5)
	v_pk_mul_f32 v[94:95], v[94:95], v[60:61]
	v_pk_mul_f32 v[96:97], v[96:97], v[62:63]
	s_waitcnt vmcnt(4)
	v_pk_mul_f32 v[98:99], v[98:99], v[64:65]
	v_pk_mul_f32 v[100:101], v[100:101], v[66:67]
	s_waitcnt vmcnt(3)
	v_pk_mul_f32 v[102:103], v[102:103], v[68:69]
	v_pk_mul_f32 v[104:105], v[104:105], v[70:71]
	s_waitcnt vmcnt(2)
	v_pk_mul_f32 v[106:107], v[106:107], v[72:73]
	v_pk_mul_f32 v[108:109], v[108:109], v[74:75]
	s_waitcnt vmcnt(1)
	v_pk_mul_f32 v[110:111], v[110:111], v[76:77]
	v_pk_mul_f32 v[112:113], v[112:113], v[78:79]
	s_waitcnt vmcnt(0)
	v_pk_mul_f32 v[114:115], v[114:115], v[82:83]
; __device__ __forceinline__ unsigned cvt_pk_bf16(float lo, float hi) { f32x2 v = {lo, hi}; bf16x2_t b = __builtin_convertvector(v, bf16x2_t); return __builtin_bit_cast(unsigned, b); }
; #define LAS __attribute__((address_space(3)))
; template <int MODE, int K, int N>
; __device__ __forceinline__ void conv_blocked(const float* __restrict__ W, bf16* D, const float* __restrict__ gk, unsigned gtid, unsigned nthr, LAS unsigned char* scr  ) {
;     ...
;         const int rho = pg8::p32inv(lane & 31), half = lane >> 5;
; #pragma unroll
;         for (int c = 0; c < 4; ++c) { v4u o; o.x = cvt_pk_bf16(v[8 * c], v[8 * c + 1]); o.y = cvt_pk_bf16(v[8 * c + 2], v[8 * c + 3]); o.z = cvt_pk_bf16(v[8 * c + 4], v[8 * c + 5]); o.w = cvt_pk_bf16(v[8 * c + 6], v[8 * c + 7]);
;             *(LAS v4u*)(scr + (half * 32 + rho) * 64 + ((c * 16) ^ ((rho & 8) << 2))) = o; }
;         const int nb = n - lane;
; #pragma unroll
;         for (int i = 0; i < 4; ++i) { const int h2 = i >> 1, b2 = i & 1; const int gp = ((MODE == 1) ? nperm(nb + 32 * h2) : nb + 32 * h2) & ~31;
;             const v4u o = *(const LAS v4u*)(scr + (h2 * 32 + b2 * 16) * 64 + lane * 16);
;             *(v4u*)((unsigned char*)D + ((size_t)((gp >> 4) + b2) * (K >> 5) + (size_t)(k0 >> 5)) * 1024 + lane * 16) = o; }
;         asm volatile("s_waitcnt lgkmcnt(0)" ::: "memory");
.Lcs_40:
	s_waitcnt vmcnt(62)
	v_cvt_pk_bf16_f32 v12, v12, v13
	s_waitcnt vmcnt(60)
	v_cvt_pk_bf16_f32 v13, v14, v15
	s_waitcnt vmcnt(58)
	v_cvt_pk_bf16_f32 v14, v16, v17
	s_waitcnt vmcnt(56)
	v_cvt_pk_bf16_f32 v15, v18, v19
	ds_write_b128 v45, v[12:15]
	s_waitcnt vmcnt(54)
	v_cvt_pk_bf16_f32 v12, v20, v21
	s_waitcnt vmcnt(52)
	v_cvt_pk_bf16_f32 v13, v22, v23
	s_waitcnt vmcnt(50)
	v_cvt_pk_bf16_f32 v14, v24, v25
	s_waitcnt vmcnt(48)
	v_cvt_pk_bf16_f32 v15, v26, v27
	ds_write_b128 v45, v[12:15] offset:16
	s_waitcnt vmcnt(46)
	v_cvt_pk_bf16_f32 v12, v28, v29
	s_waitcnt vmcnt(44)
	v_cvt_pk_bf16_f32 v13, v30, v31
	s_waitcnt vmcnt(42)
	v_cvt_pk_bf16_f32 v14, v32, v33
	s_waitcnt vmcnt(40)
	v_cvt_pk_bf16_f32 v15, v34, v35
	ds_write_b128 v46, v[12:15]
	s_waitcnt vmcnt(38)
	v_cvt_pk_bf16_f32 v12, v36, v37
	s_waitcnt vmcnt(36)
	v_cvt_pk_bf16_f32 v13, v38, v39
	s_waitcnt vmcnt(34)
	v_cvt_pk_bf16_f32 v14, v42, v43
	s_waitcnt vmcnt(32)
	v_cvt_pk_bf16_f32 v15, v40, v41
	v_lshrrev_b32_e32 v6, 4, v49
	ds_write_b128 v46, v[12:15] offset:16
	v_sub_u32_e32 v24, v50, v2
	v_and_b32_e32 v6, 0x1fc00, v6
	v_lshl_add_u64 v[20:21], v[10:11], 0, v[6:7]
	ds_read_b128 v[12:15], v47
	v_ashrrev_i32_e32 v6, 4, v24
	v_and_b32_e32 v16, -2, v6
	v_ashrrev_i32_e32 v17, 31, v16
	v_lshlrev_b64 v[16:17], 17, v[16:17]
	v_lshl_add_u64 v[22:23], v[20:21], 0, v[16:17]
	ds_read_b128 v[16:19], v47 offset:1024
	s_waitcnt lgkmcnt(1)
	global_store_dwordx4 v[22:23], v[12:15], off
	s_nop 1
	v_or_b32_e32 v12, 1, v6
	v_ashrrev_i32_e32 v13, 31, v12
	v_lshlrev_b64 v[12:13], 17, v[12:13]
	v_lshl_add_u64 v[12:13], v[20:21], 0, v[12:13]
	v_add_u32_e32 v6, 32, v24
	s_waitcnt lgkmcnt(0)
	global_store_dwordx4 v[12:13], v[16:19], off
	ds_read_b128 v[12:15], v47 offset:2048
	v_ashrrev_i32_e32 v6, 4, v6
	v_and_b32_e32 v16, -2, v6
	v_ashrrev_i32_e32 v17, 31, v16
	v_lshlrev_b64 v[16:17], 17, v[16:17]
	v_lshl_add_u64 v[22:23], v[20:21], 0, v[16:17]
	ds_read_b128 v[16:19], v47 offset:3072
	s_waitcnt lgkmcnt(1)
	global_store_dwordx4 v[22:23], v[12:15], off
	s_nop 0
	s_nop 0
	v_or_b32_e32 v12, 1, v6
	v_ashrrev_i32_e32 v13, 31, v12
	v_lshlrev_b64 v[12:13], 17, v[12:13]
	v_lshl_add_u64 v[12:13], v[20:21], 0, v[12:13]
	s_waitcnt lgkmcnt(0)
	global_store_dwordx4 v[12:13], v[16:19], off
	s_waitcnt lgkmcnt(0)
	s_waitcnt vmcnt(30)
	v_cvt_pk_bf16_f32 v86, v86, v87
	s_waitcnt vmcnt(28)
	v_cvt_pk_bf16_f32 v87, v88, v89
	s_waitcnt vmcnt(26)
	v_cvt_pk_bf16_f32 v88, v90, v91
	s_waitcnt vmcnt(24)
	v_cvt_pk_bf16_f32 v89, v92, v93
	ds_write_b128 v45, v[86:89]
	s_waitcnt vmcnt(22)
	v_cvt_pk_bf16_f32 v86, v94, v95
	s_waitcnt vmcnt(20)
	v_cvt_pk_bf16_f32 v87, v96, v97
	s_waitcnt vmcnt(18)
	v_cvt_pk_bf16_f32 v88, v98, v99
	s_waitcnt vmcnt(16)
	v_cvt_pk_bf16_f32 v89, v100, v101
	ds_write_b128 v45, v[86:89] offset:16
	s_waitcnt vmcnt(14)
	v_cvt_pk_bf16_f32 v86, v102, v103
	s_waitcnt vmcnt(12)
	v_cvt_pk_bf16_f32 v87, v104, v105
	s_waitcnt vmcnt(10)
	v_cvt_pk_bf16_f32 v88, v106, v107
	s_waitcnt vmcnt(8)
	v_cvt_pk_bf16_f32 v89, v108, v109
	ds_write_b128 v46, v[86:89]
	s_waitcnt vmcnt(6)
	v_cvt_pk_bf16_f32 v86, v110, v111
	s_waitcnt vmcnt(4)
	v_cvt_pk_bf16_f32 v87, v112, v113
	s_waitcnt vmcnt(2)
	v_cvt_pk_bf16_f32 v88, v116, v117
	s_waitcnt vmcnt(0)
	v_cvt_pk_bf16_f32 v89, v114, v115
	v_lshrrev_b32_e32 v84, 4, v119
	ds_write_b128 v46, v[86:89] offset:16
	v_sub_u32_e32 v98, v120, v2
	v_and_b32_e32 v84, 0x1fc00, v84
	v_lshl_add_u64 v[94:95], v[10:11], 0, v[84:85]
	ds_read_b128 v[86:89], v47
	v_ashrrev_i32_e32 v84, 4, v98
	v_and_b32_e32 v90, -2, v84
	v_ashrrev_i32_e32 v91, 31, v90
	v_lshlrev_b64 v[90:91], 17, v[90:91]
	v_lshl_add_u64 v[96:97], v[94:95], 0, v[90:91]
	ds_read_b128 v[90:93], v47 offset:1024
	s_waitcnt lgkmcnt(1)
	s_and_saveexec_b64 s[96:97], s[98:99]
	global_store_dwordx4 v[96:97], v[86:89], off
	s_mov_b64 exec, s[96:97]
	v_add_u32_e32 v119, s0, v119
	v_cmp_lt_u32_e32 vcc, s63, v119
	v_or_b32_e32 v86, 1, v84
	v_ashrrev_i32_e32 v87, 31, v86
	v_lshlrev_b64 v[86:87], 17, v[86:87]
	v_lshl_add_u64 v[86:87], v[94:95], 0, v[86:87]
	v_add_u32_e32 v84, 32, v98
	s_waitcnt lgkmcnt(0)
	s_and_saveexec_b64 s[96:97], s[98:99]
	global_store_dwordx4 v[86:87], v[90:93], off
	s_mov_b64 exec, s[96:97]
	ds_read_b128 v[86:89], v47 offset:2048
	v_ashrrev_i32_e32 v84, 4, v84
	v_and_b32_e32 v90, -2, v84
	v_ashrrev_i32_e32 v91, 31, v90
	v_lshlrev_b64 v[90:91], 17, v[90:91]
	v_lshl_add_u64 v[96:97], v[94:95], 0, v[90:91]
	ds_read_b128 v[90:93], v47 offset:3072
	s_waitcnt lgkmcnt(1)
	s_and_saveexec_b64 s[96:97], s[98:99]
	global_store_dwordx4 v[96:97], v[86:89], off
	s_mov_b64 exec, s[96:97]
	s_or_b64 s[48:49], vcc, s[48:49]
	s_nop 0
	v_or_b32_e32 v86, 1, v84
	v_ashrrev_i32_e32 v87, 31, v86
	v_lshlrev_b64 v[86:87], 17, v[86:87]
	v_lshl_add_u64 v[86:87], v[94:95], 0, v[86:87]
	s_waitcnt lgkmcnt(0)
	s_and_saveexec_b64 s[96:97], s[98:99]
	global_store_dwordx4 v[86:87], v[90:93], off
	s_mov_b64 exec, s[96:97]
	s_waitcnt lgkmcnt(0)
	v_mov_b32_e32 v49, v119
	s_andn2_b64 exec, exec, s[48:49]
	s_cbranch_execnz .Lcs_41
.Lcs_43:
	s_or_b64 exec, exec, s[2:3]
	s_and_saveexec_b64 s[2:3], s[6:7]
	s_cbranch_execz .Lcs_46
	s_lshl_b64 s[44:45], s[28:29], 26
	s_add_u32 s44, s16, s44
	s_addc_u32 s45, s17, s45
	v_lshl_add_u64 v[10:11], v[8:9], 0, s[40:41]
	s_mov_b64 s[46:47], 0
	v_mov_b32_e32 v12, v3
	v_mov_b32_e32 v13, v1
	v_mov_b32_e32 v85, 0
; template <int MODE, int K, int N>
; __device__ __forceinline__ void conv_blocked(const float* __restrict__ W, bf16* D, const float* __restrict__ gk, unsigned gtid, unsigned nthr, LAS unsigned char* scr  ) {
;     ...
;     for (unsigned it = gtid; it < items; it += nthr) {
;         const unsigned kb = it / (unsigned)N; const int n = (int)(it - kb * (unsigned)N), k0 = (int)kb * 32;
;         if (MODE == 1 && n >= C_U && n < C_GB) continue;
;         const float* src = W + (size_t)k0 * N + n;
;         float v[32];
; #pragma unroll
;         for (int i = 0; i < 32; ++i) v[i] = __builtin_nontemporal_load(src + (size_t)i * N);
.Lcs_45:
	v_and_b32_e32 v6, 0xfe0000, v12
	v_and_b32_e32 v22, 0xfff, v13
	v_lshlrev_b32_e32 v6, 2, v6
	v_lshl_add_u64 v[14:15], s[44:45], 0, v[6:7]
	v_lshlrev_b32_e32 v6, 2, v22
	v_lshl_add_u64 v[14:15], v[14:15], 0, v[6:7]
	v_add_co_u32_e32 v16, vcc, 0x4000, v14
	global_load_dword v23, v[14:15], off nt
	s_nop 0
	v_addc_co_u32_e32 v17, vcc, 0, v15, vcc
	v_add_co_u32_e32 v18, vcc, 0x8000, v14
	global_load_dword v24, v[16:17], off nt
	s_nop 0
	v_addc_co_u32_e32 v19, vcc, 0, v15, vcc
	v_add_co_u32_e32 v16, vcc, 0xc000, v14
	v_lshrrev_b32_e32 v6, 2, v13
	s_nop 0
	v_addc_co_u32_e32 v17, vcc, 0, v15, vcc
	v_add_co_u32_e32 v20, vcc, 0x10000, v14
	global_load_dword v25, v[18:19], off nt
	global_load_dword v26, v[16:17], off nt
	v_addc_co_u32_e32 v21, vcc, 0, v15, vcc
	v_add_co_u32_e32 v16, vcc, 0x14000, v14
	v_and_b32_e32 v6, 0x1fc00, v6
	s_nop 0
	v_addc_co_u32_e32 v17, vcc, 0, v15, vcc
	v_add_co_u32_e32 v18, vcc, 0x18000, v14
	global_load_dword v27, v[20:21], off nt
	global_load_dword v28, v[16:17], off nt
	v_addc_co_u32_e32 v19, vcc, 0, v15, vcc
	v_add_co_u32_e32 v16, vcc, 0x1c000, v14
	v_lshl_add_u64 v[30:31], v[10:11], 0, v[6:7]
	s_nop 0
	v_addc_co_u32_e32 v17, vcc, 0, v15, vcc
	v_add_co_u32_e32 v20, vcc, 0x20000, v14
	global_load_dword v29, v[18:19], off nt
	global_load_dword v40, v[16:17], off nt
	v_addc_co_u32_e32 v21, vcc, 0, v15, vcc
	v_add_co_u32_e32 v16, vcc, 0x24000, v14
	v_add_u32_e32 v13, s0, v13
	s_nop 0
	v_addc_co_u32_e32 v17, vcc, 0, v15, vcc
	v_add_co_u32_e32 v18, vcc, 0x28000, v14
	global_load_dword v41, v[20:21], off nt
	global_load_dword v42, v[16:17], off nt
	v_addc_co_u32_e32 v19, vcc, 0, v15, vcc
	v_add_co_u32_e32 v16, vcc, 0x2c000, v14
	v_add_u32_e32 v12, s62, v12
	s_nop 0
	v_addc_co_u32_e32 v17, vcc, 0, v15, vcc
	v_add_co_u32_e32 v20, vcc, 0x30000, v14
	global_load_dword v43, v[18:19], off nt
	global_load_dword v49, v[16:17], off nt
	v_addc_co_u32_e32 v21, vcc, 0, v15, vcc
	v_add_co_u32_e32 v16, vcc, 0x34000, v14
	s_nop 1
	v_addc_co_u32_e32 v17, vcc, 0, v15, vcc
	v_add_co_u32_e32 v18, vcc, 0x38000, v14
	global_load_dword v50, v[20:21], off nt
	global_load_dword v51, v[16:17], off nt
	v_addc_co_u32_e32 v19, vcc, 0, v15, vcc
	v_add_co_u32_e32 v16, vcc, 0x3c000, v14
	s_nop 1
	v_addc_co_u32_e32 v17, vcc, 0, v15, vcc
	v_add_co_u32_e32 v20, vcc, 0x40000, v14
	global_load_dword v52, v[18:19], off nt
	global_load_dword v53, v[16:17], off nt
	v_addc_co_u32_e32 v21, vcc, 0, v15, vcc
	v_add_co_u32_e32 v16, vcc, 0x44000, v14
	s_nop 1
	v_addc_co_u32_e32 v17, vcc, 0, v15, vcc
	v_add_co_u32_e32 v18, vcc, 0x48000, v14
	global_load_dword v54, v[20:21], off nt
	global_load_dword v55, v[16:17], off nt
	v_addc_co_u32_e32 v19, vcc, 0, v15, vcc
	v_add_co_u32_e32 v16, vcc, 0x4c000, v14
	s_nop 1
	v_addc_co_u32_e32 v17, vcc, 0, v15, vcc
	v_add_co_u32_e32 v20, vcc, 0x50000, v14
	global_load_dword v56, v[18:19], off nt
	global_load_dword v57, v[16:17], off nt
	v_addc_co_u32_e32 v21, vcc, 0, v15, vcc
	v_add_co_u32_e32 v16, vcc, 0x54000, v14
	s_nop 1
	v_addc_co_u32_e32 v17, vcc, 0, v15, vcc
	v_add_co_u32_e32 v18, vcc, 0x58000, v14
	global_load_dword v58, v[20:21], off nt
	global_load_dword v59, v[16:17], off nt
	v_addc_co_u32_e32 v19, vcc, 0, v15, vcc
	v_add_co_u32_e32 v16, vcc, 0x5c000, v14
	s_nop 1
	v_addc_co_u32_e32 v17, vcc, 0, v15, vcc
	v_add_co_u32_e32 v20, vcc, 0x60000, v14
	global_load_dword v60, v[18:19], off nt
	global_load_dword v61, v[16:17], off nt
	v_addc_co_u32_e32 v21, vcc, 0, v15, vcc
	v_add_co_u32_e32 v16, vcc, 0x64000, v14
	s_nop 1
	v_addc_co_u32_e32 v17, vcc, 0, v15, vcc
	v_add_co_u32_e32 v18, vcc, 0x68000, v14
	global_load_dword v62, v[20:21], off nt
	global_load_dword v63, v[16:17], off nt
	v_addc_co_u32_e32 v19, vcc, 0, v15, vcc
	v_add_co_u32_e32 v16, vcc, 0x6c000, v14
	s_nop 1
	v_addc_co_u32_e32 v17, vcc, 0, v15, vcc
	v_add_co_u32_e32 v20, vcc, 0x70000, v14
	global_load_dword v64, v[18:19], off nt
	global_load_dword v65, v[16:17], off nt
	v_addc_co_u32_e32 v21, vcc, 0, v15, vcc
	v_add_co_u32_e32 v16, vcc, 0x74000, v14
	s_nop 1
	v_addc_co_u32_e32 v17, vcc, 0, v15, vcc
	v_add_co_u32_e32 v18, vcc, 0x78000, v14
	global_load_dword v66, v[20:21], off nt
	global_load_dword v67, v[16:17], off nt
	v_addc_co_u32_e32 v19, vcc, 0, v15, vcc
	v_add_co_u32_e32 v14, vcc, 0x7c000, v14
	s_nop 1
	v_addc_co_u32_e32 v15, vcc, 0, v15, vcc
	global_load_dword v68, v[18:19], off nt
	global_load_dword v69, v[14:15], off nt
	v_cmp_ge_u32_e32 vcc, s66, v13
	v_subrev_u32_e32 v86, s62, v12
	v_subrev_u32_e32 v87, s0, v13
	s_mov_b64 s[98:99], vcc
	v_cndmask_b32_e32 v86, v86, v12, vcc
	v_cndmask_b32_e32 v87, v87, v13, vcc
	v_add_u32_e32 v13, s0, v13
	v_add_u32_e32 v12, s62, v12
	v_and_b32_e32 v84, 0xfe0000, v86
	v_and_b32_e32 v96, 0xfff, v87
	v_lshlrev_b32_e32 v84, 2, v84
	v_lshl_add_u64 v[88:89], s[44:45], 0, v[84:85]
	v_lshlrev_b32_e32 v84, 2, v96
	v_lshl_add_u64 v[88:89], v[88:89], 0, v[84:85]
	v_add_co_u32_e32 v90, vcc, 0x4000, v88
	global_load_dword v97, v[88:89], off nt
	s_nop 0
	v_addc_co_u32_e32 v91, vcc, 0, v89, vcc
	v_add_co_u32_e32 v92, vcc, 0x8000, v88
	global_load_dword v98, v[90:91], off nt
	s_nop 0
	v_addc_co_u32_e32 v93, vcc, 0, v89, vcc
	v_add_co_u32_e32 v90, vcc, 0xc000, v88
	v_lshrrev_b32_e32 v84, 2, v87
	s_nop 0
	v_addc_co_u32_e32 v91, vcc, 0, v89, vcc
	v_add_co_u32_e32 v94, vcc, 0x10000, v88
	global_load_dword v99, v[92:93], off nt
	global_load_dword v100, v[90:91], off nt
	v_addc_co_u32_e32 v95, vcc, 0, v89, vcc
	v_add_co_u32_e32 v90, vcc, 0x14000, v88
	v_and_b32_e32 v84, 0x1fc00, v84
	s_nop 0
	v_addc_co_u32_e32 v91, vcc, 0, v89, vcc
	v_add_co_u32_e32 v92, vcc, 0x18000, v88
	global_load_dword v101, v[94:95], off nt
; __device__ __forceinline__ unsigned cvt_pk_bf16(float lo, float hi) { f32x2 v = {lo, hi}; bf16x2_t b = __builtin_convertvector(v, bf16x2_t); return __builtin_bit_cast(unsigned, b); }
; #define LAS __attribute__((address_space(3)))
; template <int MODE, int K, int N>
; __device__ __forceinline__ void conv_blocked(const float* __restrict__ W, bf16* D, const float* __restrict__ gk, unsigned gtid, unsigned nthr, LAS unsigned char* scr  ) {
;     ...
;         const float* src = W + (size_t)k0 * N + n;
;         float v[32];
; #pragma unroll
;         for (int i = 0; i < 32; ++i) v[i] = __builtin_nontemporal_load(src + (size_t)i * N);
;         if (gk) {
; #pragma unroll
;             for (int i = 0; i < 32; ++i) v[i] *= gk[k0 + i];
;         }
;         const int rho = pg8::p32inv(lane & 31), half = lane >> 5;
; #pragma unroll
;         for (int c = 0; c < 4; ++c) { v4u o; o.x = cvt_pk_bf16(v[8 * c], v[8 * c + 1]); o.y = cvt_pk_bf16(v[8 * c + 2], v[8 * c + 3]); o.z = cvt_pk_bf16(v[8 * c + 4], v[8 * c + 5]); o.w = cvt_pk_bf16(v[8 * c + 6], v[8 * c + 7]);
;             *(LAS v4u*)(scr + (half * 32 + rho) * 64 + ((c * 16) ^ ((rho & 8) << 2))) = o; }
;         const int nb = n - lane;
; #pragma unroll
;         for (int i = 0; i < 4; ++i) { const int h2 = i >> 1, b2 = i & 1; const int gp = ((MODE == 1) ? nperm(nb + 32 * h2) : nb + 32 * h2) & ~31;
;             const v4u o = *(const LAS v4u*)(scr + (h2 * 32 + b2 * 16) * 64 + lane * 16);
;             *(v4u*)((unsigned char*)D + ((size_t)((gp >> 4) + b2) * (K >> 5) + (size_t)(k0 >> 5)) * 1024 + lane * 16) = o; }
	global_load_dword v102, v[90:91], off nt
	v_addc_co_u32_e32 v93, vcc, 0, v89, vcc
	v_add_co_u32_e32 v90, vcc, 0x1c000, v88
	v_lshl_add_u64 v[104:105], v[10:11], 0, v[84:85]
	s_nop 0
	v_addc_co_u32_e32 v91, vcc, 0, v89, vcc
	v_add_co_u32_e32 v94, vcc, 0x20000, v88
	global_load_dword v103, v[92:93], off nt
	global_load_dword v114, v[90:91], off nt
	v_addc_co_u32_e32 v95, vcc, 0, v89, vcc
	v_add_co_u32_e32 v90, vcc, 0x24000, v88
	v_add_u32_e32 v87, s0, v87
	s_nop 0
	v_addc_co_u32_e32 v91, vcc, 0, v89, vcc
	v_add_co_u32_e32 v92, vcc, 0x28000, v88
	global_load_dword v115, v[94:95], off nt
	global_load_dword v116, v[90:91], off nt
	v_addc_co_u32_e32 v93, vcc, 0, v89, vcc
	v_add_co_u32_e32 v90, vcc, 0x2c000, v88
	v_add_u32_e32 v86, s62, v86
	s_nop 0
	v_addc_co_u32_e32 v91, vcc, 0, v89, vcc
	v_add_co_u32_e32 v94, vcc, 0x30000, v88
	global_load_dword v117, v[92:93], off nt
	global_load_dword v119, v[90:91], off nt
	v_addc_co_u32_e32 v95, vcc, 0, v89, vcc
	v_add_co_u32_e32 v90, vcc, 0x34000, v88
	s_nop 1
	v_addc_co_u32_e32 v91, vcc, 0, v89, vcc
	v_add_co_u32_e32 v92, vcc, 0x38000, v88
	global_load_dword v120, v[94:95], off nt
	global_load_dword v121, v[90:91], off nt
	v_addc_co_u32_e32 v93, vcc, 0, v89, vcc
	v_add_co_u32_e32 v90, vcc, 0x3c000, v88
	s_nop 1
	v_addc_co_u32_e32 v91, vcc, 0, v89, vcc
	v_add_co_u32_e32 v94, vcc, 0x40000, v88
	global_load_dword v122, v[92:93], off nt
	global_load_dword v123, v[90:91], off nt
	v_addc_co_u32_e32 v95, vcc, 0, v89, vcc
	v_add_co_u32_e32 v90, vcc, 0x44000, v88
	s_nop 1
	v_addc_co_u32_e32 v91, vcc, 0, v89, vcc
	v_add_co_u32_e32 v92, vcc, 0x48000, v88
	global_load_dword v124, v[94:95], off nt
	global_load_dword v125, v[90:91], off nt
	v_addc_co_u32_e32 v93, vcc, 0, v89, vcc
	v_add_co_u32_e32 v90, vcc, 0x4c000, v88
	s_nop 1
	v_addc_co_u32_e32 v91, vcc, 0, v89, vcc
	v_add_co_u32_e32 v94, vcc, 0x50000, v88
	global_load_dword v126, v[92:93], off nt
	global_load_dword v127, v[90:91], off nt
	v_addc_co_u32_e32 v95, vcc, 0, v89, vcc
	v_add_co_u32_e32 v90, vcc, 0x54000, v88
	s_nop 1
	v_addc_co_u32_e32 v91, vcc, 0, v89, vcc
	v_add_co_u32_e32 v92, vcc, 0x58000, v88
	global_load_dword v128, v[94:95], off nt
	global_load_dword v129, v[90:91], off nt
	v_addc_co_u32_e32 v93, vcc, 0, v89, vcc
	v_add_co_u32_e32 v90, vcc, 0x5c000, v88
	s_nop 1
	v_addc_co_u32_e32 v91, vcc, 0, v89, vcc
	v_add_co_u32_e32 v94, vcc, 0x60000, v88
	global_load_dword v130, v[92:93], off nt
	global_load_dword v131, v[90:91], off nt
	v_addc_co_u32_e32 v95, vcc, 0, v89, vcc
	v_add_co_u32_e32 v90, vcc, 0x64000, v88
	s_nop 1
	v_addc_co_u32_e32 v91, vcc, 0, v89, vcc
	v_add_co_u32_e32 v92, vcc, 0x68000, v88
	global_load_dword v132, v[94:95], off nt
	global_load_dword v133, v[90:91], off nt
	v_addc_co_u32_e32 v93, vcc, 0, v89, vcc
	v_add_co_u32_e32 v90, vcc, 0x6c000, v88
	s_nop 1
	v_addc_co_u32_e32 v91, vcc, 0, v89, vcc
	v_add_co_u32_e32 v94, vcc, 0x70000, v88
	global_load_dword v134, v[92:93], off nt
	global_load_dword v135, v[90:91], off nt
	v_addc_co_u32_e32 v95, vcc, 0, v89, vcc
	v_add_co_u32_e32 v90, vcc, 0x74000, v88
	s_nop 1
	v_addc_co_u32_e32 v91, vcc, 0, v89, vcc
	v_add_co_u32_e32 v92, vcc, 0x78000, v88
	s_waitcnt vmcnt(59)
	global_load_dword v136, v[94:95], off nt
	global_load_dword v137, v[90:91], off nt
	v_addc_co_u32_e32 v93, vcc, 0, v89, vcc
	v_add_co_u32_e32 v88, vcc, 0x7c000, v88
	s_nop 1
	v_addc_co_u32_e32 v89, vcc, 0, v89, vcc
	global_load_dword v138, v[92:93], off nt
	global_load_dword v139, v[88:89], off nt
	v_sub_u32_e32 v14, v22, v2
	v_ashrrev_i32_e32 v15, 4, v14
	v_add_u32_e32 v17, 32, v14
	v_and_b32_e32 v14, -2, v15
	v_ashrrev_i32_e32 v19, 4, v17
	v_or_b32_e32 v16, 1, v15
	v_ashrrev_i32_e32 v15, 31, v14
	v_and_b32_e32 v18, -2, v19
	v_ashrrev_i32_e32 v17, 31, v16
	v_or_b32_e32 v20, 1, v19
	v_lshlrev_b64 v[14:15], 17, v[14:15]
	v_ashrrev_i32_e32 v19, 31, v18
	v_lshlrev_b64 v[16:17], 17, v[16:17]
	v_lshl_add_u64 v[32:33], v[30:31], 0, v[14:15]
	v_lshlrev_b64 v[14:15], 17, v[18:19]
	v_lshl_add_u64 v[34:35], v[30:31], 0, v[16:17]
	v_lshl_add_u64 v[38:39], v[30:31], 0, v[14:15]
	s_waitcnt vmcnt(62)
; __device__ __forceinline__ unsigned cvt_pk_bf16(float lo, float hi) { f32x2 v = {lo, hi}; bf16x2_t b = __builtin_convertvector(v, bf16x2_t); return __builtin_bit_cast(unsigned, b); }
; #define LAS __attribute__((address_space(3)))
; template <int MODE, int K, int N>
; __device__ __forceinline__ void conv_blocked(const float* __restrict__ W, bf16* D, const float* __restrict__ gk, unsigned gtid, unsigned nthr, LAS unsigned char* scr  ) {
;     ...
;         const int rho = pg8::p32inv(lane & 31), half = lane >> 5;
; #pragma unroll
;         for (int c = 0; c < 4; ++c) { v4u o; o.x = cvt_pk_bf16(v[8 * c], v[8 * c + 1]); o.y = cvt_pk_bf16(v[8 * c + 2], v[8 * c + 3]); o.z = cvt_pk_bf16(v[8 * c + 4], v[8 * c + 5]); o.w = cvt_pk_bf16(v[8 * c + 6], v[8 * c + 7]);
;             *(LAS v4u*)(scr + (half * 32 + rho) * 64 + ((c * 16) ^ ((rho & 8) << 2))) = o; }
;         const int nb = n - lane;
; #pragma unroll
;         for (int i = 0; i < 4; ++i) { const int h2 = i >> 1, b2 = i & 1; const int gp = ((MODE == 1) ? nperm(nb + 32 * h2) : nb + 32 * h2) & ~31;
;             const v4u o = *(const LAS v4u*)(scr + (h2 * 32 + b2 * 16) * 64 + lane * 16);
;             *(v4u*)((unsigned char*)D + ((size_t)((gp >> 4) + b2) * (K >> 5) + (size_t)(k0 >> 5)) * 1024 + lane * 16) = o; }
;         asm volatile("s_waitcnt lgkmcnt(0)" ::: "memory");
	v_cvt_pk_bf16_f32 v14, v23, v24
	s_waitcnt vmcnt(60)
	v_cvt_pk_bf16_f32 v15, v25, v26
	s_waitcnt vmcnt(58)
	v_cvt_pk_bf16_f32 v16, v27, v28
	s_waitcnt vmcnt(56)
	v_cvt_pk_bf16_f32 v17, v29, v40
	ds_write_b128 v45, v[14:17]
	s_waitcnt vmcnt(54)
	v_cvt_pk_bf16_f32 v14, v41, v42
	s_waitcnt vmcnt(52)
	v_cvt_pk_bf16_f32 v15, v43, v49
	s_waitcnt vmcnt(50)
	v_cvt_pk_bf16_f32 v16, v50, v51
	s_waitcnt vmcnt(48)
	v_cvt_pk_bf16_f32 v17, v52, v53
	ds_write_b128 v45, v[14:17] offset:16
	s_waitcnt vmcnt(46)
	v_cvt_pk_bf16_f32 v14, v54, v55
	s_waitcnt vmcnt(44)
	v_cvt_pk_bf16_f32 v15, v56, v57
	v_ashrrev_i32_e32 v21, 31, v20
	v_lshlrev_b64 v[36:37], 17, v[20:21]
	s_waitcnt vmcnt(42)
	v_cvt_pk_bf16_f32 v16, v58, v59
	v_lshl_add_u64 v[30:31], v[30:31], 0, v[36:37]
	s_waitcnt vmcnt(40)
	v_cvt_pk_bf16_f32 v17, v60, v61
	ds_write_b128 v46, v[14:17]
	s_waitcnt vmcnt(38)
	v_cvt_pk_bf16_f32 v14, v62, v63
	s_waitcnt vmcnt(36)
	v_cvt_pk_bf16_f32 v15, v64, v65
	s_waitcnt vmcnt(34)
	v_cvt_pk_bf16_f32 v16, v66, v67
	s_waitcnt vmcnt(32)
	v_cvt_pk_bf16_f32 v17, v68, v69
	ds_write_b128 v46, v[14:17] offset:16
	ds_read_b128 v[14:17], v47
	ds_read_b128 v[18:21], v47 offset:1024
	ds_read_b128 v[22:25], v47 offset:2048
	ds_read_b128 v[26:29], v47 offset:3072
	s_waitcnt lgkmcnt(3)
	global_store_dwordx4 v[32:33], v[14:17], off
	s_waitcnt lgkmcnt(2)
	global_store_dwordx4 v[34:35], v[18:21], off
	s_waitcnt lgkmcnt(1)
	global_store_dwordx4 v[38:39], v[22:25], off
	s_waitcnt lgkmcnt(0)
	global_store_dwordx4 v[30:31], v[26:29], off
	s_waitcnt lgkmcnt(0)
	v_sub_u32_e32 v88, v96, v2
	v_ashrrev_i32_e32 v89, 4, v88
	v_add_u32_e32 v91, 32, v88
	v_and_b32_e32 v88, -2, v89
	v_ashrrev_i32_e32 v93, 4, v91
	v_or_b32_e32 v90, 1, v89
	v_ashrrev_i32_e32 v89, 31, v88
	v_and_b32_e32 v92, -2, v93
	v_ashrrev_i32_e32 v91, 31, v90
	v_or_b32_e32 v94, 1, v93
	v_lshlrev_b64 v[88:89], 17, v[88:89]
	v_ashrrev_i32_e32 v93, 31, v92
	v_lshlrev_b64 v[90:91], 17, v[90:91]
	v_lshl_add_u64 v[106:107], v[104:105], 0, v[88:89]
	v_lshlrev_b64 v[88:89], 17, v[92:93]
	v_lshl_add_u64 v[108:109], v[104:105], 0, v[90:91]
	v_lshl_add_u64 v[112:113], v[104:105], 0, v[88:89]
	s_waitcnt vmcnt(30)
	v_cvt_pk_bf16_f32 v88, v97, v98
	s_waitcnt vmcnt(28)
	v_cvt_pk_bf16_f32 v89, v99, v100
	s_waitcnt vmcnt(26)
	v_cvt_pk_bf16_f32 v90, v101, v102
	s_waitcnt vmcnt(24)
	v_cvt_pk_bf16_f32 v91, v103, v114
	ds_write_b128 v45, v[88:91]
	s_waitcnt vmcnt(22)
	v_cvt_pk_bf16_f32 v88, v115, v116
	s_waitcnt vmcnt(20)
	v_cvt_pk_bf16_f32 v89, v117, v119
	s_waitcnt vmcnt(18)
	v_cvt_pk_bf16_f32 v90, v120, v121
	s_waitcnt vmcnt(16)
	v_cvt_pk_bf16_f32 v91, v122, v123
	ds_write_b128 v45, v[88:91] offset:16
	s_waitcnt vmcnt(14)
	v_cvt_pk_bf16_f32 v88, v124, v125
	s_waitcnt vmcnt(12)
	v_cvt_pk_bf16_f32 v89, v126, v127
	v_ashrrev_i32_e32 v95, 31, v94
	v_lshlrev_b64 v[110:111], 17, v[94:95]
	s_waitcnt vmcnt(10)
	v_cvt_pk_bf16_f32 v90, v128, v129
	v_lshl_add_u64 v[104:105], v[104:105], 0, v[110:111]
	v_cmp_lt_u32_e32 vcc, s66, v87
	s_or_b64 s[46:47], vcc, s[46:47]
	s_waitcnt vmcnt(8)
	v_cvt_pk_bf16_f32 v91, v130, v131
	ds_write_b128 v46, v[88:91]
	s_waitcnt vmcnt(6)
	v_cvt_pk_bf16_f32 v88, v132, v133
	s_waitcnt vmcnt(4)
	v_cvt_pk_bf16_f32 v89, v134, v135
	s_waitcnt vmcnt(2)
	v_cvt_pk_bf16_f32 v90, v136, v137
	s_waitcnt vmcnt(0)
	v_cvt_pk_bf16_f32 v91, v138, v139
	ds_write_b128 v46, v[88:91] offset:16
	ds_read_b128 v[88:91], v47
	ds_read_b128 v[92:95], v47 offset:1024
	ds_read_b128 v[96:99], v47 offset:2048
	ds_read_b128 v[100:103], v47 offset:3072
	s_and_saveexec_b64 s[96:97], s[98:99]
	s_waitcnt lgkmcnt(3)
	global_store_dwordx4 v[106:107], v[88:91], off
	s_waitcnt lgkmcnt(2)
	global_store_dwordx4 v[108:109], v[92:95], off
	s_waitcnt lgkmcnt(1)
	global_store_dwordx4 v[112:113], v[96:99], off
	s_waitcnt lgkmcnt(0)
	global_store_dwordx4 v[104:105], v[100:103], off
	s_mov_b64 exec, s[96:97]
	s_waitcnt lgkmcnt(0)
	s_andn2_b64 exec, exec, s[46:47]
	s_cbranch_execnz .Lcs_45

; __device__ __forceinline__ void p0_prologue(const __attribute__((address_space(4))) Args* ka, unsigned char* ws, unsigned gtid, unsigned nthr, int gw, int ngw, int lane, LAS unsigned char* scr) {
;     ...
;     for (int l2 = 0; l2 < DEPTH * PROBE_P0; ++l2) { const int l = DEPTH - 1 - (l2 % DEPTH);
;         unsigned char* wl = ws + WS_W + (size_t)l * W_LAYER;
;         conv_blocked<0, DFF, DM>(in[11] + (size_t)l * DFF * DM, (bf16*)(wl + W_DN), nullptr, gtid, nthr, scr);
;         conv_blocked<0, DM, DFF>(in[10] + (size_t)l * DM * DFF, (bf16*)(wl + W_UP), in[4] + l * DM, gtid, nthr, scr);
;         conv_blocked<0, DM, DM>(in[2] + (size_t)l * DM * DM, (bf16*)(wl + W_OUT), nullptr, gtid, nthr, scr);
;         conv_blocked<1, DM, NIN>(in[1] + (size_t)l * DM * NIN, (bf16*)(wl + W_IN), in[3] + l * DM, gtid, nthr, scr);
;     }
.Lcs_end:
	s_cmp_eq_u32 s101, 0
	s_cbranch_scc1 .Lret_A
	s_cmp_eq_u32 s101, 1
	s_cbranch_scc1 .Lret_M

; #define LAS __attribute__((address_space(3)))
; __global__ void __launch_bounds__(NWAVES * 64, 2) fwd(Args args_unused) {
;     extern __shared__ __attribute__((aligned(16))) unsigned char lds[];
;     LAS unsigned char* const ldsp = (LAS unsigned char*)lds;
;     { const int tid0 = threadIdx.x; for (int u = tid0; u < (LDS_BYTES - LDSCTL_OFF) / 4; u += NWAVES * 64) ((LAS unsigned*)(ldsp + LDSCTL_OFF))[u] = 0u; }
	.amdhsa_kernel _Z3fwd4Args
		.amdhsa_group_segment_fixed_size 512
		.amdhsa_private_segment_fixed_size 0
		.amdhsa_kernarg_size 384
		.amdhsa_user_sgpr_count 2
		.amdhsa_user_sgpr_dispatch_ptr 0
		.amdhsa_user_sgpr_queue_ptr 0
		.amdhsa_user_sgpr_kernarg_segment_ptr 1
		.amdhsa_user_sgpr_dispatch_id 0
		.amdhsa_user_sgpr_kernarg_preload_length 0
		.amdhsa_user_sgpr_kernarg_preload_offset 0
		.amdhsa_user_sgpr_private_segment_size 0
		.amdhsa_uses_dynamic_stack 0
		.amdhsa_enable_private_segment 0
		.amdhsa_system_sgpr_workgroup_id_x 1
		.amdhsa_system_sgpr_workgroup_id_y 0
		.amdhsa_system_sgpr_workgroup_id_z 0
		.amdhsa_system_sgpr_workgroup_info 0
		.amdhsa_system_vgpr_workitem_id 0
		.amdhsa_next_free_vgpr 256
		.amdhsa_next_free_sgpr 102
		.amdhsa_accum_offset 256
		.amdhsa_reserve_vcc 1
		.amdhsa_float_round_mode_32 0
		.amdhsa_float_round_mode_16_64 0
		.amdhsa_float_denorm_mode_32 3
		.amdhsa_float_denorm_mode_16_64 3
		.amdhsa_dx10_clamp 1
		.amdhsa_ieee_mode 1
		.amdhsa_fp16_overflow 0
		.amdhsa_tg_split 0
		.amdhsa_exception_fp_ieee_invalid_op 0
		.amdhsa_exception_fp_denorm_src 0
		.amdhsa_exception_fp_ieee_div_zero 0
		.amdhsa_exception_fp_ieee_overflow 0
		.amdhsa_exception_fp_ieee_underflow 0
		.amdhsa_exception_fp_ieee_inexact 0
		.amdhsa_exception_int_div_zero 0
	.end_amdhsa_kernel

; #define LAS __attribute__((address_space(3)))
; __global__ void __launch_bounds__(NWAVES * 64, 2) fwd(Args args_unused) {
;     extern __shared__ __attribute__((aligned(16))) unsigned char lds[];
;     LAS unsigned char* const ldsp = (LAS unsigned char*)lds;
;     { const int tid0 = threadIdx.x; for (int u = tid0; u < (LDS_BYTES - LDSCTL_OFF) / 4; u += NWAVES * 64) ((LAS unsigned*)(ldsp + LDSCTL_OFF))[u] = 0u; }
amdhsa.kernels:
  - .agpr_count:     0
    .args:
      - .offset:         0
        .size:           128
        .value_kind:     by_value
      - .offset:         128
        .size:           4
        .value_kind:     hidden_block_count_x
      - .offset:         132
        .size:           4
        .value_kind:     hidden_block_count_y
      - .offset:         136
        .size:           4
        .value_kind:     hidden_block_count_z
      - .offset:         140
        .size:           2
        .value_kind:     hidden_group_size_x
      - .offset:         142
        .size:           2
        .value_kind:     hidden_group_size_y
      - .offset:         144
        .size:           2
        .value_kind:     hidden_group_size_z
      - .offset:         146
        .size:           2
        .value_kind:     hidden_remainder_x
      - .offset:         148
        .size:           2
        .value_kind:     hidden_remainder_y
      - .offset:         150
        .size:           2
        .value_kind:     hidden_remainder_z
      - .offset:         168
        .size:           8
        .value_kind:     hidden_global_offset_x
      - .offset:         176
        .size:           8
        .value_kind:     hidden_global_offset_y
      - .offset:         184
        .size:           8
        .value_kind:     hidden_global_offset_z
      - .offset:         192
        .size:           2
        .value_kind:     hidden_grid_dims
      - .offset:         248
        .size:           4
        .value_kind:     hidden_dynamic_lds_size
    .group_segment_fixed_size: 512
    .kernarg_segment_align: 8
    .kernarg_segment_size: 384
    .language:       OpenCL C
    .language_version:
      - 2
      - 0
    .max_flat_workgroup_size: 512
    .name:           _Z3fwd4Args
    .private_segment_fixed_size: 0
    .sgpr_count:     108
    .sgpr_spill_count: 26
    .symbol:         _Z3fwd4Args.kd
    .uniform_work_group_size: 1
    .uses_dynamic_stack: false
    .vgpr_count:     256
    .vgpr_spill_count: 0
    .wavefront_size: 64
